# prep_gdn: per-head decay/beta scalar loads (a_proj, b_proj, dt_bias, A_log) requested at the top of the unit loop instead of waited for in place while the other waves sit at the barrier
# speedup vs baseline: 1.0114x; 1.0029x over previous
.LBB0_258:
	v_mov_b32_e32 v38, v164
	v_mov_b32_e32 v34, v21
	v_ashrrev_i32_e32 v19, 8, v38
	v_add_u32_e32 v0, s33, v19
	v_bfe_u32 v4, v0, 7, 4
	v_bfe_u32 v136, v38, 7, 1
	v_lshlrev_b32_e32 v107, 1, v4
	v_and_b32_e32 v105, 0x7f, v0
	v_ashrrev_i32_e32 v40, 11, v0
	v_or_b32_e32 v0, v107, v136
	v_and_b32_e32 v32, 0x7f, v38
	v_readlane_b32 s100, v250, 15
	v_readlane_b32 s101, v250, 16
	v_lshrrev_b32_e32 v251, 8, v38
	v_lshlrev_b32_e32 v251, 15, v251
	v_and_b32_e32 v254, 0x80, v38
	v_lshl_add_u32 v251, v254, 6, v251
	v_lshl_add_u32 v251, v4, 9, v251
	v_lshl_add_u32 v251, v32, 2, v251
	global_load_dword v252, v251, s[100:101]
	v_add_u32_e32 v251, 0x10000, v251
	global_load_dword v253, v251, s[100:101]
	v_bfe_u32 v254, v38, 6, 2
	v_or_b32_e32 v254, v107, v254
	v_lshlrev_b32_e32 v251, 13, v40
	v_lshl_or_b32 v251, v105, 6, v251
	v_and_b32_e32 v249, 63, v38
	v_add_u32_e32 v251, v251, v249
	v_lshlrev_b32_e32 v251, 2, v251
	v_lshl_add_u32 v251, v254, 16, v251
	v_readlane_b32 s98, v250, 19
	v_readlane_b32 s99, v250, 20
	global_load_dword v246, v251, s[16:17]
	v_add_u32_e32 v251, 0x200000, v251
	v_readlane_b32 s100, v250, 17
	v_readlane_b32 s101, v250, 18
	global_load_dword v247, v251, s[16:17]
	v_lshlrev_b32_e32 v254, 2, v254
	s_nop 4
	global_load_dword v248, v254, s[98:99]
	global_load_dword v249, v254, s[100:101]
	v_lshlrev_b32_e32 v127, 7, v0
	v_or_b32_e32 v5, v127, v32
	v_or_b32_e32 v0, 0x1000, v5
	v_subrev_co_u32_e64 v1, s[0:1], 1, v105
	v_lshlrev_b32_e32 v8, 7, v40
	v_add_u32_e32 v1, v1, v8
	v_lshlrev_b32_e32 v20, 1, v0
	s_xor_b64 s[4:5], s[0:1], -1
	v_lshl_add_u32 v1, v1, 1, v1
	v_lshl_add_u64 v[2:3], s[14:15], 0, v[20:21]
	v_mov_b32_e32 v33, 0
	v_mov_b32_e32 v35, 0
	s_and_saveexec_b64 s[6:7], s[4:5]
	s_cbranch_execz .Lpg_hb_done
	s_movk_i32 s2, 0x5000
	v_mad_i64_i32 v[6:7], s[8:9], v1, s2, v[2:3]
	global_load_short_d16_hi v34, v[6:7], off
	v_add_co_u32_e32 v6, vcc, 0x5000, v6
	s_nop 1
	v_addc_co_u32_e32 v7, vcc, 0, v7, vcc
	global_load_short_d16_hi v35, v[6:7], off
	v_add_co_u32_e32 v6, vcc, 0x5000, v6
	s_nop 1
	v_addc_co_u32_e32 v7, vcc, 0, v7, vcc
	global_load_short_d16_hi v33, v[6:7], off
.Lpg_hb_done:
	s_or_b64 exec, exec, s[6:7]
	v_ashrrev_i32_e32 v41, 31, v40
	v_lshlrev_b64 v[36:37], 13, v[40:41]
	v_lshlrev_b32_e32 v20, 1, v0
	v_lshl_or_b32 v22, v105, 6, v36
	v_lshl_add_u64 v[2:3], s[68:69], 0, v[20:21]
	v_mad_u64_u32 v[2:3], s[4:5], v22, s29, v[2:3]
	v_mad_i32_i24 v3, v37, s29, v3
	v_add_co_u32_e32 v6, vcc, s29, v2
	global_load_ushort v84, v[2:3], off
	s_nop 0
	v_addc_co_u32_e32 v7, vcc, 0, v3, vcc
	global_load_ushort v85, v[6:7], off
	v_add_co_u32_e32 v6, vcc, s30, v2
	s_mov_b32 s2, 0x12000
	s_nop 0
	v_addc_co_u32_e32 v7, vcc, 0, v3, vcc
	global_load_ushort v99, v[6:7], off
	v_add_co_u32_e32 v6, vcc, s2, v2
	s_mov_b32 s2, 0x18000
	s_nop 0
	v_addc_co_u32_e32 v7, vcc, 0, v3, vcc
	global_load_ushort v104, v[6:7], off
	v_add_co_u32_e32 v6, vcc, s2, v2
	s_mov_b32 s2, 0x84000
	s_nop 0
	v_addc_co_u32_e32 v7, vcc, 0, v3, vcc
	global_load_ushort v91, v[6:7], off
	v_add_co_u32_e32 v6, vcc, s35, v2
	v_readlane_b32 s36, v250, 3
	s_nop 0
	v_addc_co_u32_e32 v7, vcc, 0, v3, vcc
	global_load_ushort v101, v[6:7], off
	v_add_co_u32_e32 v6, vcc, s60, v2
	v_mov_b32_e32 v1, v21
	s_nop 0
	v_addc_co_u32_e32 v7, vcc, 0, v3, vcc
	global_load_ushort v88, v[6:7], off
	v_add_co_u32_e32 v6, vcc, s61, v2
	v_readlane_b32 s48, v250, 15
	s_nop 0
	v_addc_co_u32_e32 v7, vcc, 0, v3, vcc
	global_load_ushort v93, v[6:7], off
	v_add_co_u32_e32 v6, vcc, s66, v2
	v_readlane_b32 s49, v250, 16
	s_nop 0
	v_addc_co_u32_e32 v7, vcc, 0, v3, vcc
	global_load_ushort v96, v[6:7], off
	v_add_co_u32_e32 v6, vcc, s67, v2
	v_lshl_add_u64 v[0:1], v[0:1], 2, s[48:49]
	s_nop 0
	v_addc_co_u32_e32 v7, vcc, 0, v3, vcc
	global_load_ushort v97, v[6:7], off
	v_add_co_u32_e32 v6, vcc, s64, v2
	v_lshlrev_b32_e32 v20, 2, v5
	s_nop 0
	v_addc_co_u32_e32 v7, vcc, 0, v3, vcc
	global_load_ushort v83, v[6:7], off
	v_add_co_u32_e32 v6, vcc, s65, v2
	global_load_dword v28, v[0:1], off
	s_nop 0
	v_addc_co_u32_e32 v7, vcc, 0, v3, vcc
	global_load_ushort v89, v[6:7], off
	v_add_co_u32_e32 v6, vcc, s74, v2
	v_lshl_add_u64 v[0:1], s[48:49], 0, v[20:21]
	s_nop 0
	v_addc_co_u32_e32 v7, vcc, 0, v3, vcc
	global_load_ushort v78, v[6:7], off
	v_add_co_u32_e32 v6, vcc, s75, v2
	v_lshlrev_b32_e32 v27, 7, v4
	s_nop 0
	v_addc_co_u32_e32 v7, vcc, 0, v3, vcc
	global_load_ushort v81, v[6:7], off
	v_add_co_u32_e32 v6, vcc, s59, v2
	v_readlane_b32 s37, v250, 4
	s_nop 0
	v_addc_co_u32_e32 v7, vcc, 0, v3, vcc
	global_load_ushort v70, v[6:7], off
	v_add_co_u32_e32 v6, vcc, s22, v2
	v_readlane_b32 s38, v250, 5
	s_nop 0
	v_addc_co_u32_e32 v7, vcc, 0, v3, vcc
	global_load_ushort v73, v[6:7], off
	v_add_co_u32_e32 v6, vcc, s23, v2
	v_readlane_b32 s39, v250, 6
	s_nop 0
	v_addc_co_u32_e32 v7, vcc, 0, v3, vcc
	global_load_ushort v75, v[6:7], off
	v_add_co_u32_e32 v6, vcc, s12, v2
	v_readlane_b32 s40, v250, 7
	s_nop 0
	v_addc_co_u32_e32 v7, vcc, 0, v3, vcc
	global_load_ushort v79, v[6:7], off
	v_add_co_u32_e32 v6, vcc, s13, v2
	v_readlane_b32 s41, v250, 8
	s_nop 0
	v_addc_co_u32_e32 v7, vcc, 0, v3, vcc
	global_load_ushort v67, v[6:7], off
	v_add_co_u32_e32 v6, vcc, s28, v2
	v_readlane_b32 s42, v250, 9
	s_nop 0
	v_addc_co_u32_e32 v7, vcc, 0, v3, vcc
	global_load_ushort v71, v[6:7], off
	v_add_co_u32_e32 v6, vcc, s52, v2
	v_readlane_b32 s43, v250, 10
	s_nop 0
	v_addc_co_u32_e32 v7, vcc, 0, v3, vcc
	global_load_ushort v50, v[6:7], off
	v_add_co_u32_e32 v6, vcc, s53, v2
	v_readlane_b32 s44, v250, 11
	s_nop 0
	v_addc_co_u32_e32 v7, vcc, 0, v3, vcc
	global_load_ushort v65, v[6:7], off
	v_add_co_u32_e32 v6, vcc, s2, v2
	s_mov_b32 s2, 0x8a000
	s_nop 0
	v_addc_co_u32_e32 v7, vcc, 0, v3, vcc
	global_load_ushort v41, v[6:7], off
	v_add_co_u32_e32 v6, vcc, s2, v2
	s_mov_b32 s2, 0x90000
	s_nop 0
	v_addc_co_u32_e32 v7, vcc, 0, v3, vcc
	global_load_ushort v51, v[6:7], off
	v_add_co_u32_e32 v6, vcc, s2, v2
	s_mov_b32 s2, 0x96000
	s_nop 0
	v_addc_co_u32_e32 v7, vcc, 0, v3, vcc
	global_load_ushort v59, v[6:7], off
	v_add_co_u32_e32 v6, vcc, s2, v2
	s_mov_b32 s2, 0x9c000
	s_nop 0
	v_addc_co_u32_e32 v7, vcc, 0, v3, vcc
	global_load_ushort v63, v[6:7], off
	v_add_co_u32_e32 v6, vcc, s2, v2
	s_mov_b32 s2, 0xa2000
	s_nop 0
	v_addc_co_u32_e32 v7, vcc, 0, v3, vcc
	global_load_ushort v55, v[6:7], off
	v_add_co_u32_e32 v6, vcc, s2, v2
	s_mov_b32 s2, 0xa8000
	s_nop 0
	v_addc_co_u32_e32 v7, vcc, 0, v3, vcc
	global_load_ushort v58, v[6:7], off
	v_add_co_u32_e32 v6, vcc, s2, v2
	s_mov_b32 s2, 0xae000
	s_nop 0
	v_addc_co_u32_e32 v7, vcc, 0, v3, vcc
	global_load_ushort v53, v[6:7], off
	v_add_co_u32_e32 v6, vcc, s2, v2
	s_mov_b32 s2, 0xb4000
	s_nop 0
	v_addc_co_u32_e32 v7, vcc, 0, v3, vcc
	global_load_ushort v57, v[6:7], off
	v_add_co_u32_e32 v6, vcc, s2, v2
	s_mov_b32 s2, 0xba000
	s_nop 0
	v_addc_co_u32_e32 v7, vcc, 0, v3, vcc
	global_load_ushort v52, v[6:7], off
	v_add_co_u32_e32 v6, vcc, s2, v2
	s_mov_b32 s2, 0xc0000
	s_nop 0
	v_addc_co_u32_e32 v7, vcc, 0, v3, vcc
	global_load_ushort v54, v[6:7], off
	v_add_co_u32_e32 v6, vcc, s2, v2
	s_mov_b32 s2, 0xc6000
	s_nop 0
	v_addc_co_u32_e32 v7, vcc, 0, v3, vcc
	global_load_ushort v56, v[6:7], off
	v_add_co_u32_e32 v6, vcc, s2, v2
	s_mov_b32 s2, 0xcc000
	s_nop 0
	v_addc_co_u32_e32 v7, vcc, 0, v3, vcc
	global_load_ushort v62, v[6:7], off
	v_add_co_u32_e32 v6, vcc, s2, v2
	s_mov_b32 s2, 0xd2000
	s_nop 0
	v_addc_co_u32_e32 v7, vcc, 0, v3, vcc
	global_load_ushort v60, v[6:7], off
	v_add_co_u32_e32 v6, vcc, s2, v2
	s_mov_b32 s2, 0xd8000
	s_nop 0
	v_addc_co_u32_e32 v7, vcc, 0, v3, vcc
	global_load_ushort v61, v[6:7], off
	v_add_co_u32_e32 v6, vcc, s2, v2
	s_mov_b32 s2, 0xde000
	s_nop 0
	v_addc_co_u32_e32 v7, vcc, 0, v3, vcc
	global_load_ushort v64, v[6:7], off
	v_add_co_u32_e32 v6, vcc, s2, v2
	s_mov_b32 s2, 0xe4000
	s_nop 0
	v_addc_co_u32_e32 v7, vcc, 0, v3, vcc
	global_load_ushort v66, v[6:7], off
	v_add_co_u32_e32 v6, vcc, s2, v2
	s_mov_b32 s2, 0xea000
	s_nop 0
	v_addc_co_u32_e32 v7, vcc, 0, v3, vcc
	global_load_ushort v68, v[6:7], off
	v_add_co_u32_e32 v6, vcc, s2, v2
	s_mov_b32 s2, 0xf0000
	s_nop 0
	v_addc_co_u32_e32 v7, vcc, 0, v3, vcc
	global_load_ushort v69, v[6:7], off
	v_add_co_u32_e32 v6, vcc, s2, v2
	s_mov_b32 s2, 0xf6000
	s_nop 0
	v_addc_co_u32_e32 v7, vcc, 0, v3, vcc
	global_load_ushort v72, v[6:7], off
	v_add_co_u32_e32 v6, vcc, s2, v2
	s_mov_b32 s2, 0xfc000
	s_nop 0
	v_addc_co_u32_e32 v7, vcc, 0, v3, vcc
	global_load_ushort v74, v[6:7], off
	v_add_co_u32_e32 v6, vcc, s2, v2
	s_mov_b32 s2, 0x102000
	s_nop 0
	v_addc_co_u32_e32 v7, vcc, 0, v3, vcc
	global_load_ushort v76, v[6:7], off
	v_add_co_u32_e32 v6, vcc, s2, v2
	s_mov_b32 s2, 0x108000
	s_nop 0
	v_addc_co_u32_e32 v7, vcc, 0, v3, vcc
	global_load_ushort v77, v[6:7], off
	v_add_co_u32_e32 v6, vcc, s2, v2
	s_mov_b32 s2, 0x10e000
	s_nop 0
	v_addc_co_u32_e32 v7, vcc, 0, v3, vcc
	global_load_ushort v80, v[6:7], off
	v_add_co_u32_e32 v6, vcc, s2, v2
	s_mov_b32 s2, 0x114000
	s_nop 0
	v_addc_co_u32_e32 v7, vcc, 0, v3, vcc
	global_load_ushort v82, v[6:7], off
	v_add_co_u32_e32 v6, vcc, s2, v2
	s_mov_b32 s2, 0x11a000
	s_nop 0
	v_addc_co_u32_e32 v7, vcc, 0, v3, vcc
	global_load_ushort v86, v[6:7], off
	v_add_co_u32_e32 v6, vcc, s2, v2
	s_mov_b32 s2, 0x120000
	s_nop 0
	v_addc_co_u32_e32 v7, vcc, 0, v3, vcc
	global_load_ushort v87, v[6:7], off
	v_add_co_u32_e32 v6, vcc, s2, v2
	s_mov_b32 s2, 0x126000
	s_nop 0
	v_addc_co_u32_e32 v7, vcc, 0, v3, vcc
	global_load_ushort v90, v[6:7], off
	v_add_co_u32_e32 v6, vcc, s2, v2
	s_mov_b32 s2, 0x12c000
	s_nop 0
	v_addc_co_u32_e32 v7, vcc, 0, v3, vcc
	global_load_ushort v92, v[6:7], off
	v_add_co_u32_e32 v6, vcc, s2, v2
	s_mov_b32 s2, 0x132000
	s_nop 0
	v_addc_co_u32_e32 v7, vcc, 0, v3, vcc
	global_load_ushort v94, v[6:7], off
	v_add_co_u32_e32 v6, vcc, s2, v2
	s_mov_b32 s2, 0x138000
	s_nop 0
	v_addc_co_u32_e32 v7, vcc, 0, v3, vcc
	global_load_ushort v95, v[6:7], off
	v_add_co_u32_e32 v6, vcc, s2, v2
	s_mov_b32 s2, 0x13e000
	s_nop 0
	v_addc_co_u32_e32 v7, vcc, 0, v3, vcc
	global_load_ushort v98, v[6:7], off
	v_add_co_u32_e32 v6, vcc, s2, v2
	s_mov_b32 s2, 0x144000
	s_nop 0
	v_addc_co_u32_e32 v7, vcc, 0, v3, vcc
	global_load_ushort v100, v[6:7], off
	v_add_co_u32_e32 v6, vcc, s2, v2
	s_mov_b32 s2, 0x14a000
	s_nop 0
	v_addc_co_u32_e32 v7, vcc, 0, v3, vcc
	global_load_ushort v102, v[6:7], off
	v_add_co_u32_e32 v6, vcc, s2, v2
	s_mov_b32 s2, 0x150000
	s_nop 0
	v_addc_co_u32_e32 v7, vcc, 0, v3, vcc
	global_load_ushort v103, v[6:7], off
	v_add_co_u32_e32 v6, vcc, s2, v2
	s_mov_b32 s2, 0x156000
	s_nop 0
	v_addc_co_u32_e32 v7, vcc, 0, v3, vcc
	global_load_ushort v106, v[6:7], off
	v_add_co_u32_e32 v6, vcc, s2, v2
	s_mov_b32 s2, 0x15c000
	s_nop 0
	v_addc_co_u32_e32 v7, vcc, 0, v3, vcc
	global_load_ushort v116, v[6:7], off
	v_add_co_u32_e32 v6, vcc, s2, v2
	s_mov_b32 s2, 0x162000
	s_nop 0
	v_addc_co_u32_e32 v7, vcc, 0, v3, vcc
	global_load_ushort v142, v[6:7], off
	v_add_co_u32_e32 v6, vcc, s2, v2
	s_mov_b32 s2, 0x168000
	s_nop 0
	v_addc_co_u32_e32 v7, vcc, 0, v3, vcc
	global_load_ushort v143, v[6:7], off
	v_add_co_u32_e32 v6, vcc, s2, v2
	s_mov_b32 s2, 0x16e000
	s_nop 0
	v_addc_co_u32_e32 v7, vcc, 0, v3, vcc
	global_load_ushort v138, v[6:7], off
	v_add_co_u32_e32 v6, vcc, s2, v2
	s_mov_b32 s2, 0x174000
	s_nop 0
	v_addc_co_u32_e32 v7, vcc, 0, v3, vcc
	global_load_ushort v139, v[6:7], off
	v_add_co_u32_e32 v6, vcc, s2, v2
	s_mov_b32 s2, 0x17a000
	s_nop 0
	v_addc_co_u32_e32 v7, vcc, 0, v3, vcc
	v_add_co_u32_e32 v2, vcc, s2, v2
	global_load_ushort v137, v[6:7], off
	s_nop 0
	v_addc_co_u32_e32 v3, vcc, 0, v3, vcc
	global_load_ushort v207, v[2:3], off
	v_add_co_u32_e32 v2, vcc, s30, v0
	s_movk_i32 s2, 0x400
	s_nop 0
	v_addc_co_u32_e32 v3, vcc, 0, v1, vcc
	global_load_dword v29, v[2:3], off
	v_add_co_u32_e32 v2, vcc, 0x14000, v0
	v_readlane_b32 s45, v250, 12
	s_nop 0
	v_addc_co_u32_e32 v3, vcc, 0, v1, vcc
	v_add_co_u32_e32 v0, vcc, 0x1c000, v0
	global_load_dword v30, v[2:3], off
	s_nop 0
	v_addc_co_u32_e32 v1, vcc, 0, v1, vcc
	global_load_dword v31, v[0:1], off
	v_cmp_gt_i32_e32 vcc, s2, v38
	v_readlane_b32 s46, v250, 13
	v_readlane_b32 s47, v250, 14
	v_readlane_b32 s50, v250, 17
	v_readlane_b32 s51, v250, 18
	s_waitcnt vmcnt(63) expcnt(7) lgkmcnt(15)
	s_barrier
	s_waitcnt vmcnt(63)
	v_lshlrev_b32_e32 v251, 2, v38
	ds_write_b32 v251, v252
	ds_write_b32 v251, v253 offset:2048
	v_readlane_b32 s36, v250, 3
	v_readlane_b32 s37, v250, 4
	v_readlane_b32 s38, v250, 5
	v_readlane_b32 s39, v250, 6
	v_readlane_b32 s40, v250, 7
	v_readlane_b32 s41, v250, 8
	v_readlane_b32 s42, v250, 9
	v_readlane_b32 s43, v250, 10
	v_readlane_b32 s44, v250, 11
	v_readlane_b32 s45, v250, 12
	v_readlane_b32 s46, v250, 13
	v_readlane_b32 s47, v250, 14
	v_readlane_b32 s48, v250, 15
	v_readlane_b32 s49, v250, 16
	v_readlane_b32 s50, v250, 17
	v_readlane_b32 s51, v250, 18
	v_sub_u32_e64 v0, v105, 1 clamp
	v_and_b32_e32 v194, 0xff, v38
	v_or_b32_e32 v12, v0, v8
	v_lshlrev_b32_e32 v39, 6, v105
	v_mad_i64_i32 v[16:17], s[4:5], v12, 3, 0
	v_lshrrev_b32_e32 v24, 4, v194
	v_or_b32_e32 v36, v36, v39
	v_cmp_lt_u32_e32 vcc, 47, v194
	v_mov_b64_e32 v[4:5], 0x20600000
	v_mov_b64_e32 v[2:3], 0x5000
	v_add_u32_e32 v18, -3, v24
	v_mov_b32_e32 v6, v24
	v_mov_b64_e32 v[8:9], v[16:17]
	s_waitcnt lgkmcnt(0)
	s_barrier
	s_and_saveexec_b64 s[4:5], vcc
	v_mov_b64_e32 v[4:5], 0x8100000
	v_mov_b64_e32 v[2:3], 0x6000
	v_mov_b32_e32 v6, v18
	v_mov_b64_e32 v[8:9], v[36:37]
	s_or_b64 exec, exec, s[4:5]
	v_lshlrev_b32_e32 v195, 3, v38
	v_and_b32_e32 v25, 0x78, v195
	v_or_b32_e32 v113, v27, v25
	v_lshlrev_b32_e32 v20, 1, v113
	v_lshl_add_u64 v[4:5], s[82:83], 0, v[4:5]
	v_mov_b32_e32 v7, v21
	v_lshl_add_u64 v[4:5], v[4:5], 0, v[20:21]
	v_lshl_add_u64 v[6:7], v[8:9], 0, v[6:7]
	v_mad_u64_u32 v[4:5], s[4:5], v6, v2, v[4:5]
	v_mov_b32_e32 v6, v5
	v_mad_u64_u32 v[2:3], s[4:5], v7, v2, v[6:7]
	v_cmp_lt_u32_e64 s[4:5], 31, v194
	v_lshl_add_u64 v[0:1], s[14:15], 0, v[20:21]
	v_lshl_add_u64 v[48:49], s[68:69], 0, v[20:21]
	v_cndmask_b32_e64 v10, 1, -2, s[4:5]
	v_mov_b32_e32 v5, v2
	v_cndmask_b32_e64 v3, v17, v37, s[4:5]
	v_cndmask_b32_e64 v2, v16, v36, s[4:5]
	v_add_u32_e32 v20, v10, v24
	v_cndmask_b32_e64 v114, v189, v190, s[4:5]
	v_cndmask_b32_e64 v9, v1, v49, s[4:5]
	v_cndmask_b32_e64 v8, v0, v48, s[4:5]
	v_lshl_add_u64 v[46:47], v[2:3], 0, v[20:21]
	v_mul_lo_u32 v20, v47, v114
	v_mad_u64_u32 v[2:3], s[6:7], v46, v114, v[8:9]
	v_add_u32_e32 v3, v20, v3
	global_load_dwordx4 v[4:7], v[4:5], off
	v_cmp_lt_u32_e64 s[6:7], 15, v194
	global_load_dwordx4 v[8:11], v[2:3], off
	v_add_u32_e32 v42, -1, v24
	s_and_saveexec_b64 s[8:9], s[6:7]
	s_xor_b64 s[8:9], exec, s[8:9]
	v_mov_b32_e32 v43, v21
	v_lshl_add_u64 v[0:1], v[36:37], 0, v[42:43]
	v_mad_u64_u32 v[2:3], s[10:11], v0, s29, v[48:49]
	v_mov_b32_e32 v0, v3
	v_mad_u64_u32 v[0:1], s[10:11], v1, s29, v[0:1]
	v_mov_b32_e32 v3, v0
	s_or_saveexec_b64 s[8:9], s[8:9]
	s_mov_b32 s2, 0xf000
	v_mad_i64_i32 v[44:45], s[10:11], v12, s2, 0
	s_xor_b64 exec, exec, s[8:9]
	v_lshl_add_u64 v[0:1], v[0:1], 0, v[44:45]
	s_mov_b64 s[10:11], 0xa000
	v_lshl_add_u64 v[2:3], v[0:1], 0, s[10:11]
	s_or_b64 exec, exec, s[8:9]
	v_or_b32_e32 v115, v36, v24
	global_load_dwordx4 v[12:15], v[2:3], off
	v_mul_lo_u32 v112, v37, s29
	v_mad_u64_u32 v[0:1], s[8:9], v115, s29, v[48:49]
	v_add_u32_e32 v1, v112, v1
	global_load_dwordx4 v[0:3], v[0:1], off
	v_or_b32_e32 v244, 0x100, v194
	v_lshrrev_b32_e32 v245, 4, v244
	v_add_u32_e32 v208, -3, v245
	v_add_u32_e32 v210, -2, v245
	v_or_b32_e32 v208, v36, v208
	v_or_b32_e32 v210, v36, v210
	v_add_u32_e32 v212, -1, v245
	v_mad_u64_u32 v[208:209], s[100:101], v208, s29, v[48:49]
	v_mad_u64_u32 v[210:211], s[100:101], v210, s29, v[48:49]
	v_or_b32_e32 v212, v36, v212
	v_add_u32_e32 v209, v112, v209
	v_add_u32_e32 v211, v112, v211
	v_mad_u64_u32 v[212:213], s[100:101], v212, s29, v[48:49]
	v_or_b32_e32 v220, v36, v245
	global_load_dwordx4 v[216:219], v[208:209], off
	s_nop 0
	global_load_dwordx4 v[208:211], v[210:211], off
	v_add_u32_e32 v213, v112, v213
	v_mad_u64_u32 v[220:221], s[100:101], v220, s29, v[48:49]
	global_load_dwordx4 v[212:215], v[212:213], off
	v_add_u32_e32 v221, v112, v221
	global_load_dwordx4 v[220:223], v[220:221], off
	v_cmp_gt_u32_e64 s[8:9], 32, v194
	v_cmp_gt_u32_e64 s[10:11], 48, v194
	v_or_b32_e32 v26, v105, v24
	s_and_b64 s[24:25], s[8:9], s[0:1]
	s_and_b64 s[10:11], s[10:11], s[0:1]
	v_lshl_add_u32 v108, v25, 2, 0
	v_cmp_eq_u32_e64 s[0:1], 0, v26
	s_waitcnt vmcnt(6)
	v_cndmask_b32_e64 v26, v8, 0, s[24:25]
	v_cndmask_b32_e64 v117, v9, 0, s[24:25]
	v_cndmask_b32_e64 v8, v11, 0, s[24:25]
	v_cndmask_b32_e64 v111, v5, 0, s[10:11]
	v_cndmask_b32_e64 v9, v6, 0, s[10:11]
	v_cndmask_b32_e64 v5, v7, 0, s[10:11]
	ds_read_b128 v[118:121], v108
	ds_read_b128 v[122:125], v108 offset:16
	ds_read_b128 v[128:131], v108 offset:1024
	ds_read_b128 v[132:135], v108 offset:1040
	ds_read_b128 v[144:147], v108 offset:2048
	ds_read_b128 v[148:151], v108 offset:2064
	ds_read_b128 v[152:155], v108 offset:3072
	ds_read_b128 v[156:159], v108 offset:3088
	v_cndmask_b32_e64 v109, v4, 0, s[10:11]
	v_cndmask_b32_e64 v110, v10, 0, s[24:25]
	v_lshlrev_b32_e32 v4, 16, v5
	v_and_b32_e32 v5, 0xffff0000, v5
	v_lshlrev_b32_e32 v6, 16, v8
	v_and_b32_e32 v7, 0xffff0000, v8
	v_lshlrev_b32_e32 v8, 16, v9
	v_and_b32_e32 v9, 0xffff0000, v9
	v_lshlrev_b32_e32 v10, 16, v110
	v_and_b32_e32 v11, 0xffff0000, v110
	v_lshlrev_b32_e32 v110, 16, v111
	v_and_b32_e32 v111, 0xffff0000, v111
	s_waitcnt lgkmcnt(6)
	v_pk_fma_f32 v[4:5], v[124:125], v[4:5], 0 op_sel_hi:[1,1,0]
	v_pk_fma_f32 v[8:9], v[122:123], v[8:9], 0 op_sel_hi:[1,1,0]
	v_lshlrev_b32_e32 v140, 16, v117
	v_and_b32_e32 v141, 0xffff0000, v117
	v_pk_fma_f32 v[110:111], v[120:121], v[110:111], 0 op_sel_hi:[1,1,0]
	s_waitcnt lgkmcnt(4)
	v_pk_fma_f32 v[4:5], v[134:135], v[6:7], v[4:5]
	v_pk_fma_f32 v[6:7], v[132:133], v[10:11], v[8:9]
	v_pk_fma_f32 v[8:9], v[130:131], v[140:141], v[110:111]
	v_or_b32_e32 v197, 0x100, v194
	v_and_b32_e32 v47, 64, v191
	v_lshrrev_b32_e32 v198, 4, v197
	v_xor_b32_e32 v23, 1, v191
	v_add_u32_e32 v43, 64, v47
	v_cmp_lt_i32_e64 s[8:9], v23, v43
	v_mul_i32_i24_e32 v19, 0x10e00, v19
	v_add_u32_e32 v196, 0, v19
	v_cndmask_b32_e64 v23, v191, v23, s[8:9]
	v_lshlrev_b32_e32 v23, 2, v23
	v_mul_u32_u24_e32 v201, 0x110, v24
	v_or_b32_e32 v199, 0x200, v194
	v_lshrrev_b32_e32 v200, 4, v199
	v_mul_u32_u24_e32 v204, 0x110, v198
	v_or_b32_e32 v202, 0x300, v194
	v_lshrrev_b32_e32 v203, 4, v202
	v_mul_u32_u24_e32 v205, 0x110, v200
	v_mul_u32_u24_e32 v206, 0x110, v203
	s_waitcnt vmcnt(5)
	v_cndmask_b32_e64 v11, v15, 0, s[0:1]
	v_cndmask_b32_e64 v110, v13, 0, s[0:1]
	v_cndmask_b32_e64 v13, v14, 0, s[0:1]
	v_lshlrev_b32_e32 v10, 16, v11
	v_and_b32_e32 v11, 0xffff0000, v11
	v_cndmask_b32_e64 v117, v12, 0, s[0:1]
	v_lshlrev_b32_e32 v12, 16, v13
	v_and_b32_e32 v13, 0xffff0000, v13
	v_lshlrev_b32_e32 v14, 16, v110
	v_and_b32_e32 v15, 0xffff0000, v110
	s_waitcnt lgkmcnt(2)
	v_pk_fma_f32 v[4:5], v[150:151], v[10:11], v[4:5]
	s_waitcnt vmcnt(4)
	v_lshlrev_b32_e32 v10, 16, v3
	v_and_b32_e32 v11, 0xffff0000, v3
	v_pk_fma_f32 v[6:7], v[148:149], v[12:13], v[6:7]
	v_pk_fma_f32 v[8:9], v[146:147], v[14:15], v[8:9]
	v_lshlrev_b32_e32 v12, 16, v2
	v_and_b32_e32 v13, 0xffff0000, v2
	v_lshlrev_b32_e32 v2, 16, v1
	v_and_b32_e32 v3, 0xffff0000, v1
	s_waitcnt lgkmcnt(0)
	v_pk_fma_f32 v[4:5], v[158:159], v[10:11], v[4:5]
	v_pk_fma_f32 v[6:7], v[156:157], v[12:13], v[6:7]
	v_pk_fma_f32 v[110:111], v[154:155], v[2:3], v[8:9]
	v_mul_f32_e32 v1, 0xbfb8aa3b, v4
	v_mul_f32_e32 v2, 0xbfb8aa3b, v5
	v_mul_f32_e32 v3, 0xbfb8aa3b, v6
	v_exp_f32_e32 v1, v1
	v_exp_f32_e32 v2, v2
	v_exp_f32_e32 v3, v3
	v_mul_f32_e32 v9, 0xbfb8aa3b, v110
	v_exp_f32_e32 v11, v9
	v_add_f32_e32 v1, 1.0, v1
	v_add_f32_e32 v9, 1.0, v2
	v_add_f32_e32 v12, 1.0, v3
	v_rcp_f32_e32 v2, v1
	v_rcp_f32_e32 v3, v9
	v_mul_f32_e32 v8, 0xbfb8aa3b, v7
	v_exp_f32_e32 v8, v8
	v_mul_f32_e32 v10, 0xbfb8aa3b, v111
	v_pk_mul_f32 v[120:121], v[4:5], v[2:3]
	v_add_f32_e32 v2, 1.0, v11
	v_rcp_f32_e32 v130, v2
	v_lshlrev_b32_e32 v2, 16, v109
	v_and_b32_e32 v3, 0xffff0000, v109
	v_pk_fma_f32 v[2:3], v[118:119], v[2:3], 0 op_sel_hi:[1,1,0]
	v_lshlrev_b32_e32 v4, 16, v26
	v_and_b32_e32 v5, 0xffff0000, v26
	v_pk_fma_f32 v[2:3], v[128:129], v[4:5], v[2:3]
	v_lshlrev_b32_e32 v4, 16, v117
	v_and_b32_e32 v5, 0xffff0000, v117
	v_add_f32_e32 v1, 1.0, v8
	v_pk_fma_f32 v[2:3], v[144:145], v[4:5], v[2:3]
	v_lshlrev_b32_e32 v4, 16, v0
	v_and_b32_e32 v5, 0xffff0000, v0
	v_rcp_f32_e32 v9, v1
	v_exp_f32_e32 v1, v10
	v_pk_fma_f32 v[118:119], v[152:153], v[4:5], v[2:3]
	v_rcp_f32_e32 v8, v12
	v_mul_f32_e32 v0, 0xbfb8aa3b, v118
	v_exp_f32_e32 v26, v0
	v_add_f32_e32 v126, 1.0, v1
	v_pk_mul_f32 v[124:125], v[6:7], v[8:9]
	s_nop 0
	v_add_u32_e32 v226, -3, v200
	v_add_u32_e32 v228, -2, v200
	v_or_b32_e32 v226, v36, v226
	v_or_b32_e32 v228, v36, v228
	v_add_u32_e32 v230, -1, v200
	v_mad_u64_u32 v[226:227], s[100:101], v226, s29, v[48:49]
	v_mad_u64_u32 v[228:229], s[100:101], v228, s29, v[48:49]
	v_or_b32_e32 v230, v36, v230
	v_add_u32_e32 v227, v112, v227
	v_add_u32_e32 v229, v112, v229
	v_mad_u64_u32 v[230:231], s[100:101], v230, s29, v[48:49]
	v_or_b32_e32 v238, v36, v200
	global_load_dwordx4 v[234:237], v[226:227], off
	s_nop 0
	global_load_dwordx4 v[226:229], v[228:229], off
	v_add_u32_e32 v231, v112, v231
	v_mad_u64_u32 v[238:239], s[100:101], v238, s29, v[48:49]
	global_load_dwordx4 v[230:233], v[230:231], off
	v_add_u32_e32 v239, v112, v239
	global_load_dwordx4 v[238:241], v[238:239], off
	v_mul_f32_e32 v109, 0xbfb8aa3b, v119
	v_exp_f32_e32 v109, v109
	v_add_f32_e32 v26, 1.0, v26
	v_rcp_f32_e32 v128, v26
	v_rcp_f32_e32 v131, v126
	v_add_f32_e32 v26, 1.0, v109
	v_rcp_f32_e32 v129, v26
	v_pk_mul_f32 v[132:133], v[124:125], v[124:125]
	v_pk_mul_f32 v[130:131], v[110:111], v[130:131]
	v_pk_mul_f32 v[122:123], v[120:121], v[120:121]
	v_pk_mul_f32 v[118:119], v[118:119], v[128:129]
	v_pk_mul_f32 v[110:111], v[130:131], v[130:131]
	v_pk_mul_f32 v[128:129], v[118:119], v[118:119]
	v_xor_b32_e32 v109, 2, v191
	v_add_f32_e32 v26, v128, v129
	v_add_f32_e32 v26, v110, v26
	v_add_f32_e32 v26, v111, v26
	v_add_f32_e32 v26, v132, v26
	v_add_f32_e32 v26, v133, v26
	v_add_f32_e32 v26, v122, v26
	v_add_f32_e32 v26, v123, v26
	ds_bpermute_b32 v110, v23, v26
	v_cmp_lt_i32_e64 s[8:9], v109, v43
	s_waitcnt lgkmcnt(0)
	v_add_f32_e32 v26, v26, v110
	v_cndmask_b32_e64 v109, v191, v109, s[8:9]
	v_lshlrev_b32_e32 v109, 2, v109
	ds_bpermute_b32 v111, v109, v26
	v_xor_b32_e32 v110, 4, v191
	v_cmp_lt_i32_e64 s[8:9], v110, v43
	s_waitcnt lgkmcnt(0)
	v_add_f32_e32 v26, v26, v111
	v_cndmask_b32_e64 v110, v191, v110, s[8:9]
	v_lshlrev_b32_e32 v110, 2, v110
	ds_bpermute_b32 v117, v110, v26
	v_xor_b32_e32 v111, 8, v191
	v_cmp_lt_i32_e64 s[8:9], v111, v43
	s_waitcnt lgkmcnt(0)
	v_add_f32_e32 v26, v26, v117
	v_cndmask_b32_e64 v43, v191, v111, s[8:9]
	v_lshlrev_b32_e32 v111, 2, v43
	ds_bpermute_b32 v43, v111, v26
	s_waitcnt lgkmcnt(0)
	v_add_f32_e32 v26, v26, v43
	v_add_f32_e32 v26, 0x358637bd, v26
	v_mul_f32_e32 v43, 0x4b800000, v26
	v_cmp_gt_f32_e64 s[8:9], s70, v26
	s_waitcnt vmcnt(7)
	v_lshlrev_b32_e32 v140, 16, v219
	v_cndmask_b32_e64 v26, v26, v43, s[8:9]
	v_rsq_f32_e32 v26, v26
	v_and_b32_e32 v141, 0xffff0000, v219
	v_mul_f32_e32 v19, 0x45800000, v26
	v_cndmask_b32_e64 v19, v26, v19, s[8:9]
	v_mul_f32_e32 v26, 0x3db504f3, v19
	v_pk_mul_f32 v[118:119], v[118:119], v[26:27] op_sel_hi:[1,0]
	v_pk_mul_f32 v[122:123], v[130:131], v[26:27] op_sel_hi:[1,0]
	v_pk_mul_f32 v[124:125], v[124:125], v[26:27] op_sel_hi:[1,0]
	v_pk_mul_f32 v[128:129], v[120:121], v[26:27] op_sel_hi:[1,0]
	v_lshlrev_b32_e32 v26, 1, v25
	v_cvt_pk_bf16_f32 v118, v118, v119
	v_cvt_pk_bf16_f32 v119, v122, v123
	v_cvt_pk_bf16_f32 v120, v124, v125
	v_cvt_pk_bf16_f32 v121, v128, v129
	v_add3_u32 v117, v196, v201, v26
	ds_write_b128 v117, v[118:121] offset:4096
	ds_read_b128 v[118:121], v108 offset:16
	ds_read_b128 v[122:125], v108 offset:1040
	ds_read_b128 v[128:131], v108 offset:2064
	ds_read_b128 v[132:135], v108 offset:3088
	ds_read_b128 v[144:147], v108
	s_waitcnt lgkmcnt(4)
	v_pk_fma_f32 v[120:121], v[120:121], v[140:141], 0 op_sel_hi:[1,1,0]
	s_waitcnt vmcnt(6)
	v_lshlrev_b32_e32 v140, 16, v211
	v_and_b32_e32 v141, 0xffff0000, v211
	s_waitcnt lgkmcnt(3)
	v_pk_fma_f32 v[120:121], v[124:125], v[140:141], v[120:121]
	s_waitcnt vmcnt(5)
	v_lshlrev_b32_e32 v124, 16, v215
	v_and_b32_e32 v125, 0xffff0000, v215
	s_waitcnt lgkmcnt(2)
	v_pk_fma_f32 v[120:121], v[130:131], v[124:125], v[120:121]
	s_waitcnt vmcnt(4)
	v_lshlrev_b32_e32 v124, 16, v223
	v_and_b32_e32 v125, 0xffff0000, v223
	s_waitcnt lgkmcnt(1)
	v_pk_fma_f32 v[120:121], v[134:135], v[124:125], v[120:121]
	ds_read_b128 v[148:151], v108 offset:1024
	ds_read_b128 v[152:155], v108 offset:2048
	ds_read_b128 v[156:159], v108 offset:3072
	v_mul_f32_e32 v3, 0xbfb8aa3b, v120
	v_exp_f32_e32 v3, v3
	v_mul_f32_e32 v7, 0xbfb8aa3b, v121
	v_exp_f32_e32 v7, v7
	v_and_b32_e32 v15, 0xffff0000, v209
	v_add_f32_e32 v3, 1.0, v3
	v_rcp_f32_e32 v124, v3
	v_add_f32_e32 v3, 1.0, v7
	v_rcp_f32_e32 v125, v3
	v_and_b32_e32 v7, 0xffff0000, v222
	v_pk_mul_f32 v[120:121], v[120:121], v[124:125]
	v_lshlrev_b32_e32 v124, 16, v218
	v_and_b32_e32 v125, 0xffff0000, v218
	v_pk_fma_f32 v[10:11], v[118:119], v[124:125], 0 op_sel_hi:[1,1,0]
	v_lshlrev_b32_e32 v118, 16, v210
	v_and_b32_e32 v119, 0xffff0000, v210
	v_pk_fma_f32 v[2:3], v[122:123], v[118:119], v[10:11]
	v_lshlrev_b32_e32 v10, 16, v214
	v_and_b32_e32 v11, 0xffff0000, v214
	v_pk_fma_f32 v[2:3], v[128:129], v[10:11], v[2:3]
	v_lshlrev_b32_e32 v6, 16, v222
	v_pk_fma_f32 v[2:3], v[132:133], v[6:7], v[2:3]
	v_lshlrev_b32_e32 v10, 16, v217
	v_mul_f32_e32 v6, 0xbfb8aa3b, v2
	v_mul_f32_e32 v7, 0xbfb8aa3b, v3
	v_exp_f32_e32 v6, v6
	v_exp_f32_e32 v7, v7
	v_and_b32_e32 v11, 0xffff0000, v217
	s_waitcnt lgkmcnt(3)
	v_pk_fma_f32 v[10:11], v[146:147], v[10:11], 0 op_sel_hi:[1,1,0]
	v_lshlrev_b32_e32 v14, 16, v209
	s_waitcnt lgkmcnt(2)
	v_pk_fma_f32 v[10:11], v[150:151], v[14:15], v[10:11]
	v_lshlrev_b32_e32 v14, 16, v213
	v_and_b32_e32 v15, 0xffff0000, v213
	s_waitcnt lgkmcnt(1)
	v_pk_fma_f32 v[10:11], v[154:155], v[14:15], v[10:11]
	v_lshlrev_b32_e32 v14, 16, v221
	v_and_b32_e32 v15, 0xffff0000, v221
	v_add_f32_e32 v6, 1.0, v6
	v_add_f32_e32 v7, 1.0, v7
	s_waitcnt lgkmcnt(0)
	v_pk_fma_f32 v[122:123], v[158:159], v[14:15], v[10:11]
	v_rcp_f32_e32 v6, v6
	v_rcp_f32_e32 v7, v7
	v_mul_f32_e32 v1, 0xbfb8aa3b, v122
	v_exp_f32_e32 v1, v1
	v_mul_f32_e32 v5, 0xbfb8aa3b, v123
	v_pk_mul_f32 v[124:125], v[2:3], v[6:7]
	v_lshlrev_b32_e32 v2, 16, v216
	v_and_b32_e32 v3, 0xffff0000, v216
	v_add_f32_e32 v1, 1.0, v1
	v_pk_fma_f32 v[2:3], v[144:145], v[2:3], 0 op_sel_hi:[1,1,0]
	v_lshlrev_b32_e32 v6, 16, v208
	v_and_b32_e32 v7, 0xffff0000, v208
	v_rcp_f32_e32 v128, v1
	v_pk_fma_f32 v[0:1], v[148:149], v[6:7], v[2:3]
	v_lshlrev_b32_e32 v2, 16, v212
	v_and_b32_e32 v3, 0xffff0000, v212
	v_exp_f32_e32 v5, v5
	v_pk_fma_f32 v[0:1], v[152:153], v[2:3], v[0:1]
	v_lshlrev_b32_e32 v2, 16, v220
	v_and_b32_e32 v3, 0xffff0000, v220
	v_pk_fma_f32 v[130:131], v[156:157], v[2:3], v[0:1]
	v_add_f32_e32 v19, 1.0, v5
	s_nop 0
	v_add_u32_e32 v208, -3, v203
	v_add_u32_e32 v210, -2, v203
	v_or_b32_e32 v208, v36, v208
	v_or_b32_e32 v210, v36, v210
	v_add_u32_e32 v212, -1, v203
	v_mad_u64_u32 v[208:209], s[100:101], v208, s29, v[48:49]
	v_mad_u64_u32 v[210:211], s[100:101], v210, s29, v[48:49]
	v_or_b32_e32 v212, v36, v212
	v_add_u32_e32 v209, v112, v209
	v_add_u32_e32 v211, v112, v211
	v_mad_u64_u32 v[212:213], s[100:101], v212, s29, v[48:49]
	v_or_b32_e32 v220, v36, v203
	global_load_dwordx4 v[216:219], v[208:209], off
	s_nop 0
	global_load_dwordx4 v[208:211], v[210:211], off
	v_add_u32_e32 v213, v112, v213
	v_mad_u64_u32 v[220:221], s[100:101], v220, s29, v[48:49]
	global_load_dwordx4 v[212:215], v[212:213], off
	v_add_u32_e32 v221, v112, v221
	global_load_dwordx4 v[220:223], v[220:221], off
	v_mul_f32_e32 v25, 0xbfb8aa3b, v130
	v_exp_f32_e32 v25, v25
	v_mul_f32_e32 v43, 0xbfb8aa3b, v131
	v_exp_f32_e32 v43, v43
	v_rcp_f32_e32 v129, v19
	v_add_f32_e32 v19, 1.0, v25
	v_rcp_f32_e32 v132, v19
	v_add_f32_e32 v19, 1.0, v43
	v_rcp_f32_e32 v133, v19
	v_pk_mul_f32 v[122:123], v[122:123], v[128:129]
	v_pk_mul_f32 v[134:135], v[124:125], v[124:125]
	v_pk_mul_f32 v[128:129], v[122:123], v[122:123]
	v_pk_mul_f32 v[130:131], v[130:131], v[132:133]
	v_pk_mul_f32 v[118:119], v[120:121], v[120:121]
	v_pk_mul_f32 v[132:133], v[130:131], v[130:131]
	s_waitcnt vmcnt(7)
	v_lshlrev_b32_e32 v140, 16, v237
	v_add_f32_e32 v19, v132, v133
	v_add_f32_e32 v19, v128, v19
	v_add_f32_e32 v19, v129, v19
	v_add_f32_e32 v19, v134, v19
	v_add_f32_e32 v19, v135, v19
	v_add_f32_e32 v19, v118, v19
	v_add_f32_e32 v19, v119, v19
	ds_bpermute_b32 v25, v23, v19
	v_and_b32_e32 v141, 0xffff0000, v237
	s_waitcnt lgkmcnt(0)
	v_add_f32_e32 v19, v19, v25
	ds_bpermute_b32 v25, v109, v19
	s_waitcnt lgkmcnt(0)
	v_add_f32_e32 v19, v19, v25
	ds_bpermute_b32 v25, v110, v19
	s_waitcnt lgkmcnt(0)
	v_add_f32_e32 v19, v19, v25
	ds_bpermute_b32 v25, v111, v19
	s_waitcnt lgkmcnt(0)
	v_add_f32_e32 v19, v19, v25
	v_add_f32_e32 v19, 0x358637bd, v19
	v_mul_f32_e32 v25, 0x4b800000, v19
	v_cmp_gt_f32_e64 s[8:9], s70, v19
	s_nop 1
	v_cndmask_b32_e64 v19, v19, v25, s[8:9]
	v_rsq_f32_e32 v19, v19
	s_nop 0
	v_mul_f32_e32 v25, 0x45800000, v19
	v_cndmask_b32_e64 v19, v19, v25, s[8:9]
	v_mul_f32_e32 v118, 0x3db504f3, v19
	v_pk_mul_f32 v[128:129], v[130:131], v[118:119] op_sel_hi:[1,0]
	v_pk_mul_f32 v[122:123], v[122:123], v[118:119] op_sel_hi:[1,0]
	v_pk_mul_f32 v[124:125], v[124:125], v[118:119] op_sel_hi:[1,0]
	v_pk_mul_f32 v[130:131], v[120:121], v[118:119] op_sel_hi:[1,0]
	v_cvt_pk_bf16_f32 v118, v128, v129
	v_cvt_pk_bf16_f32 v119, v122, v123
	v_cvt_pk_bf16_f32 v120, v124, v125
	v_cvt_pk_bf16_f32 v121, v130, v131
	v_add3_u32 v19, v196, v204, v26
	ds_write_b128 v19, v[118:121] offset:4096
	ds_read_b128 v[118:121], v108 offset:16
	ds_read_b128 v[122:125], v108 offset:1040
	ds_read_b128 v[128:131], v108 offset:2064
	ds_read_b128 v[132:135], v108 offset:3088
	ds_read_b128 v[144:147], v108
	s_waitcnt lgkmcnt(4)
	v_pk_fma_f32 v[120:121], v[120:121], v[140:141], 0 op_sel_hi:[1,1,0]
	s_waitcnt vmcnt(6)
	v_lshlrev_b32_e32 v140, 16, v229
	v_and_b32_e32 v141, 0xffff0000, v229
	s_waitcnt lgkmcnt(3)
	v_pk_fma_f32 v[120:121], v[124:125], v[140:141], v[120:121]
	s_waitcnt vmcnt(5)
	v_lshlrev_b32_e32 v124, 16, v233
	v_and_b32_e32 v125, 0xffff0000, v233
	s_waitcnt lgkmcnt(2)
	v_pk_fma_f32 v[120:121], v[130:131], v[124:125], v[120:121]
	s_waitcnt vmcnt(4)
	v_lshlrev_b32_e32 v124, 16, v241
	v_and_b32_e32 v125, 0xffff0000, v241
	s_waitcnt lgkmcnt(1)
	v_pk_fma_f32 v[120:121], v[134:135], v[124:125], v[120:121]
	ds_read_b128 v[148:151], v108 offset:1024
	ds_read_b128 v[152:155], v108 offset:2048
	ds_read_b128 v[156:159], v108 offset:3072
	v_mul_f32_e32 v3, 0xbfb8aa3b, v120
	v_exp_f32_e32 v3, v3
	v_mul_f32_e32 v7, 0xbfb8aa3b, v121
	v_exp_f32_e32 v7, v7
	v_and_b32_e32 v15, 0xffff0000, v227
	v_add_f32_e32 v3, 1.0, v3
	v_rcp_f32_e32 v124, v3
	v_add_f32_e32 v3, 1.0, v7
	v_rcp_f32_e32 v125, v3
	v_and_b32_e32 v7, 0xffff0000, v240
	v_pk_mul_f32 v[120:121], v[120:121], v[124:125]
	v_lshlrev_b32_e32 v124, 16, v236
	v_and_b32_e32 v125, 0xffff0000, v236
	v_pk_fma_f32 v[10:11], v[118:119], v[124:125], 0 op_sel_hi:[1,1,0]
	v_lshlrev_b32_e32 v118, 16, v228
	v_and_b32_e32 v119, 0xffff0000, v228
	v_pk_fma_f32 v[2:3], v[122:123], v[118:119], v[10:11]
	v_lshlrev_b32_e32 v10, 16, v232
	v_and_b32_e32 v11, 0xffff0000, v232
	v_pk_fma_f32 v[2:3], v[128:129], v[10:11], v[2:3]
	v_lshlrev_b32_e32 v6, 16, v240
	v_pk_fma_f32 v[2:3], v[132:133], v[6:7], v[2:3]
	v_lshlrev_b32_e32 v10, 16, v235
	v_mul_f32_e32 v6, 0xbfb8aa3b, v2
	v_mul_f32_e32 v7, 0xbfb8aa3b, v3
	v_exp_f32_e32 v6, v6
	v_exp_f32_e32 v7, v7
	v_and_b32_e32 v11, 0xffff0000, v235
	s_waitcnt lgkmcnt(3)
	v_pk_fma_f32 v[10:11], v[146:147], v[10:11], 0 op_sel_hi:[1,1,0]
	v_lshlrev_b32_e32 v14, 16, v227
	s_waitcnt lgkmcnt(2)
	v_pk_fma_f32 v[10:11], v[150:151], v[14:15], v[10:11]
	v_lshlrev_b32_e32 v14, 16, v231
	v_and_b32_e32 v15, 0xffff0000, v231
	s_waitcnt lgkmcnt(1)
	v_pk_fma_f32 v[10:11], v[154:155], v[14:15], v[10:11]
	v_lshlrev_b32_e32 v14, 16, v239
	v_and_b32_e32 v15, 0xffff0000, v239
	v_add_f32_e32 v6, 1.0, v6
	v_add_f32_e32 v7, 1.0, v7
	s_waitcnt lgkmcnt(0)
	v_pk_fma_f32 v[122:123], v[158:159], v[14:15], v[10:11]
	v_rcp_f32_e32 v6, v6
	v_rcp_f32_e32 v7, v7
	v_mul_f32_e32 v1, 0xbfb8aa3b, v122
	v_exp_f32_e32 v1, v1
	v_mul_f32_e32 v5, 0xbfb8aa3b, v123
	v_pk_mul_f32 v[124:125], v[2:3], v[6:7]
	v_lshlrev_b32_e32 v2, 16, v234
	v_and_b32_e32 v3, 0xffff0000, v234
	v_add_f32_e32 v1, 1.0, v1
	v_pk_fma_f32 v[2:3], v[144:145], v[2:3], 0 op_sel_hi:[1,1,0]
	v_lshlrev_b32_e32 v6, 16, v226
	v_and_b32_e32 v7, 0xffff0000, v226
	v_rcp_f32_e32 v128, v1
	v_pk_fma_f32 v[0:1], v[148:149], v[6:7], v[2:3]
	v_lshlrev_b32_e32 v2, 16, v230
	v_and_b32_e32 v3, 0xffff0000, v230
	v_exp_f32_e32 v5, v5
	v_pk_fma_f32 v[0:1], v[152:153], v[2:3], v[0:1]
	v_lshlrev_b32_e32 v2, 16, v238
	v_and_b32_e32 v3, 0xffff0000, v238
	v_pk_fma_f32 v[130:131], v[156:157], v[2:3], v[0:1]
	v_add_f32_e32 v19, 1.0, v5
	s_nop 0
	v_mul_f32_e32 v25, 0xbfb8aa3b, v130
	v_exp_f32_e32 v25, v25
	v_mul_f32_e32 v43, 0xbfb8aa3b, v131
	v_exp_f32_e32 v43, v43
	v_rcp_f32_e32 v129, v19
	v_add_f32_e32 v19, 1.0, v25
	v_rcp_f32_e32 v48, v19
	v_add_f32_e32 v19, 1.0, v43
	v_rcp_f32_e32 v49, v19
	v_pk_mul_f32 v[122:123], v[122:123], v[128:129]
	v_pk_mul_f32 v[132:133], v[124:125], v[124:125]
	v_pk_mul_f32 v[128:129], v[122:123], v[122:123]
	v_pk_mul_f32 v[48:49], v[130:131], v[48:49]
	v_pk_mul_f32 v[118:119], v[120:121], v[120:121]
	v_pk_mul_f32 v[130:131], v[48:49], v[48:49]
	s_nop 0
	v_add_f32_e32 v19, v130, v131
	v_add_f32_e32 v19, v128, v19
	v_add_f32_e32 v19, v129, v19
	v_add_f32_e32 v19, v132, v19
	v_add_f32_e32 v19, v133, v19
	v_add_f32_e32 v19, v118, v19
	v_add_f32_e32 v19, v119, v19
	ds_bpermute_b32 v25, v23, v19
	s_waitcnt lgkmcnt(0)
	v_add_f32_e32 v19, v19, v25
	ds_bpermute_b32 v25, v109, v19
	s_waitcnt lgkmcnt(0)
	v_add_f32_e32 v19, v19, v25
	ds_bpermute_b32 v25, v110, v19
	s_waitcnt lgkmcnt(0)
	v_add_f32_e32 v19, v19, v25
	ds_bpermute_b32 v25, v111, v19
	s_waitcnt lgkmcnt(0)
	v_add_f32_e32 v19, v19, v25
	v_add_f32_e32 v19, 0x358637bd, v19
	v_mul_f32_e32 v25, 0x4b800000, v19
	v_cmp_gt_f32_e64 s[8:9], s70, v19
	s_nop 1
	v_cndmask_b32_e64 v19, v19, v25, s[8:9]
	v_rsq_f32_e32 v19, v19
	s_nop 0
	v_mul_f32_e32 v25, 0x45800000, v19
	v_cndmask_b32_e64 v19, v19, v25, s[8:9]
	v_mul_f32_e32 v118, 0x3db504f3, v19
	v_pk_mul_f32 v[48:49], v[48:49], v[118:119] op_sel_hi:[1,0]
	v_pk_mul_f32 v[122:123], v[122:123], v[118:119] op_sel_hi:[1,0]
	v_pk_mul_f32 v[124:125], v[124:125], v[118:119] op_sel_hi:[1,0]
	v_pk_mul_f32 v[128:129], v[120:121], v[118:119] op_sel_hi:[1,0]
	v_cvt_pk_bf16_f32 v118, v48, v49
	v_cvt_pk_bf16_f32 v119, v122, v123
	v_cvt_pk_bf16_f32 v120, v124, v125
	v_cvt_pk_bf16_f32 v121, v128, v129
	v_add3_u32 v19, v196, v205, v26
	ds_write_b128 v19, v[118:121] offset:4096
	ds_read_b128 v[118:121], v108 offset:16
	ds_read_b128 v[122:125], v108 offset:1040
	ds_read_b128 v[128:131], v108 offset:2064
	ds_read_b128 v[132:135], v108 offset:3088
	ds_read_b128 v[144:147], v108
	s_waitcnt vmcnt(3)
	v_lshlrev_b32_e32 v48, 16, v219
	v_and_b32_e32 v49, 0xffff0000, v219
	s_waitcnt lgkmcnt(4)
	v_pk_fma_f32 v[48:49], v[120:121], v[48:49], 0 op_sel_hi:[1,1,0]
	s_waitcnt vmcnt(2)
	v_lshlrev_b32_e32 v120, 16, v211
	v_and_b32_e32 v121, 0xffff0000, v211
	s_waitcnt lgkmcnt(3)
	v_pk_fma_f32 v[48:49], v[124:125], v[120:121], v[48:49]
	s_waitcnt vmcnt(1)
	v_lshlrev_b32_e32 v120, 16, v215
	v_and_b32_e32 v121, 0xffff0000, v215
	s_waitcnt lgkmcnt(2)
	v_pk_fma_f32 v[48:49], v[130:131], v[120:121], v[48:49]
	s_waitcnt vmcnt(0)
	v_lshlrev_b32_e32 v120, 16, v223
	v_and_b32_e32 v121, 0xffff0000, v223
	s_waitcnt lgkmcnt(1)
	v_pk_fma_f32 v[48:49], v[134:135], v[120:121], v[48:49]
	ds_read_b128 v[148:151], v108 offset:1024
	ds_read_b128 v[152:155], v108 offset:2048
	ds_read_b128 v[156:159], v108 offset:3072
	v_mul_f32_e32 v3, 0xbfb8aa3b, v48
	v_exp_f32_e32 v3, v3
	v_mul_f32_e32 v7, 0xbfb8aa3b, v49
	v_exp_f32_e32 v7, v7
	v_and_b32_e32 v15, 0xffff0000, v217
	v_add_f32_e32 v3, 1.0, v3
	v_rcp_f32_e32 v120, v3
	v_add_f32_e32 v3, 1.0, v7
	v_rcp_f32_e32 v121, v3
	v_and_b32_e32 v7, 0xffff0000, v222
	v_mov_b32_e32 v25, v21
	v_pk_mul_f32 v[48:49], v[48:49], v[120:121]
	v_lshlrev_b32_e32 v120, 16, v218
	v_and_b32_e32 v121, 0xffff0000, v218
	v_pk_fma_f32 v[10:11], v[118:119], v[120:121], 0 op_sel_hi:[1,1,0]
	v_lshlrev_b32_e32 v118, 16, v210
	v_and_b32_e32 v119, 0xffff0000, v210
	v_pk_fma_f32 v[2:3], v[122:123], v[118:119], v[10:11]
	v_lshlrev_b32_e32 v10, 16, v214
	v_and_b32_e32 v11, 0xffff0000, v214
	v_pk_fma_f32 v[2:3], v[128:129], v[10:11], v[2:3]
	v_lshlrev_b32_e32 v6, 16, v222
	v_pk_fma_f32 v[2:3], v[132:133], v[6:7], v[2:3]
	v_lshlrev_b32_e32 v14, 16, v217
	v_mul_f32_e32 v6, 0xbfb8aa3b, v2
	v_exp_f32_e32 v10, v6
	v_mul_f32_e32 v6, 0xbfb8aa3b, v3
	s_waitcnt lgkmcnt(3)
	v_pk_fma_f32 v[14:15], v[146:147], v[14:15], 0 op_sel_hi:[1,1,0]
	v_lshlrev_b32_e32 v118, 16, v209
	v_and_b32_e32 v119, 0xffff0000, v209
	v_exp_f32_e32 v11, v6
	s_waitcnt lgkmcnt(2)
	v_pk_fma_f32 v[14:15], v[150:151], v[118:119], v[14:15]
	v_lshlrev_b32_e32 v118, 16, v213
	v_and_b32_e32 v119, 0xffff0000, v213
	s_waitcnt lgkmcnt(1)
	v_pk_fma_f32 v[14:15], v[154:155], v[118:119], v[14:15]
	v_lshlrev_b32_e32 v118, 16, v221
	v_and_b32_e32 v119, 0xffff0000, v221
	s_waitcnt lgkmcnt(0)
	v_pk_fma_f32 v[14:15], v[158:159], v[118:119], v[14:15]
	v_add_f32_e32 v10, 1.0, v10
	v_mul_f32_e32 v1, 0xbfb8aa3b, v14
	v_add_f32_e32 v11, 1.0, v11
	v_exp_f32_e32 v1, v1
	v_rcp_f32_e32 v10, v10
	v_rcp_f32_e32 v11, v11
	v_mul_f32_e32 v5, 0xbfb8aa3b, v15
	v_exp_f32_e32 v5, v5
	v_lshlrev_b32_e32 v118, 16, v216
	v_and_b32_e32 v119, 0xffff0000, v216
	v_add_f32_e32 v1, 1.0, v1
	v_pk_fma_f32 v[8:9], v[144:145], v[118:119], 0 op_sel_hi:[1,1,0]
	v_lshlrev_b32_e32 v118, 16, v208
	v_and_b32_e32 v119, 0xffff0000, v208
	v_pk_mul_f32 v[2:3], v[2:3], v[10:11]
	v_rcp_f32_e32 v10, v1
	v_pk_fma_f32 v[0:1], v[148:149], v[118:119], v[8:9]
	v_lshlrev_b32_e32 v8, 16, v212
	v_and_b32_e32 v9, 0xffff0000, v212
	v_add_f32_e32 v11, 1.0, v5
	v_pk_fma_f32 v[0:1], v[152:153], v[8:9], v[0:1]
	v_lshlrev_b32_e32 v4, 16, v220
	v_and_b32_e32 v5, 0xffff0000, v220
	v_pk_fma_f32 v[0:1], v[156:157], v[4:5], v[0:1]
	v_rcp_f32_e32 v11, v11
	v_mul_f32_e32 v4, 0xbfb8aa3b, v0
	v_mul_f32_e32 v5, 0xbfb8aa3b, v1
	v_exp_f32_e32 v4, v4
	v_exp_f32_e32 v5, v5
	v_pk_mul_f32 v[10:11], v[14:15], v[10:11]
	v_pk_mul_f32 v[8:9], v[2:3], v[2:3]
	v_add_f32_e32 v4, 1.0, v4
	v_add_f32_e32 v5, 1.0, v5
	v_rcp_f32_e32 v4, v4
	v_rcp_f32_e32 v5, v5
	v_pk_mul_f32 v[12:13], v[10:11], v[10:11]
	v_pk_mul_f32 v[6:7], v[48:49], v[48:49]
	v_pk_mul_f32 v[0:1], v[0:1], v[4:5]
	s_nop 0
	v_pk_mul_f32 v[4:5], v[0:1], v[0:1]
	s_nop 0
	v_add_f32_e32 v4, v4, v5
	v_add_f32_e32 v4, v12, v4
	v_add_f32_e32 v4, v13, v4
	v_add_f32_e32 v4, v8, v4
	v_add_f32_e32 v4, v9, v4
	v_add_f32_e32 v4, v6, v4
	v_add_f32_e32 v4, v7, v4
	ds_bpermute_b32 v5, v23, v4
	s_waitcnt lgkmcnt(0)
	v_add_f32_e32 v4, v4, v5
	ds_bpermute_b32 v5, v109, v4
	s_waitcnt lgkmcnt(0)
	v_add_f32_e32 v4, v4, v5
	ds_bpermute_b32 v5, v110, v4
	s_waitcnt lgkmcnt(0)
	v_add_f32_e32 v4, v4, v5
	ds_bpermute_b32 v5, v111, v4
	s_waitcnt lgkmcnt(0)
	v_add_f32_e32 v4, v4, v5
	v_add_f32_e32 v4, 0x358637bd, v4
	v_mul_f32_e32 v5, 0x4b800000, v4
	v_cmp_gt_f32_e64 s[8:9], s70, v4
	s_nop 1
	v_cndmask_b32_e64 v4, v4, v5, s[8:9]
	v_rsq_f32_e32 v4, v4
	s_nop 0
	v_mul_f32_e32 v5, 0x45800000, v4
	v_cndmask_b32_e64 v4, v4, v5, s[8:9]
	v_mul_f32_e32 v4, 0x3db504f3, v4
	v_pk_mul_f32 v[0:1], v[0:1], v[4:5] op_sel_hi:[1,0]
	v_pk_mul_f32 v[6:7], v[10:11], v[4:5] op_sel_hi:[1,0]
	v_pk_mul_f32 v[2:3], v[2:3], v[4:5] op_sel_hi:[1,0]
	v_pk_mul_f32 v[4:5], v[48:49], v[4:5] op_sel_hi:[1,0]
	v_cvt_pk_bf16_f32 v0, v0, v1
	v_cvt_pk_bf16_f32 v1, v6, v7
	v_cvt_pk_bf16_f32 v2, v2, v3
	v_cvt_pk_bf16_f32 v3, v4, v5
	v_add3_u32 v4, v196, v206, v26
	ds_write_b128 v4, v[0:3] offset:4096
	v_mov_b64_e32 v[2:3], 0x20600000
	v_mov_b64_e32 v[0:1], 0x5000
	v_mov_b64_e32 v[4:5], v[24:25]
	s_and_saveexec_b64 s[8:9], vcc
	v_mov_b32_e32 v19, v21
	v_mov_b64_e32 v[2:3], 0x8100000
	v_mov_b64_e32 v[0:1], 0x6000
	v_mov_b64_e32 v[4:5], v[18:19]
	v_mov_b64_e32 v[16:17], v[36:37]
	s_or_b64 exec, exec, s[8:9]
	v_mad_u64_u32 v[6:7], s[8:9], v46, v114, 0
	v_add_u32_e32 v7, v7, v20
	v_lshl_or_b32 v20, v113, 1, v192
	v_lshl_add_u64 v[2:3], s[82:83], 0, v[2:3]
	v_lshl_add_u64 v[2:3], v[2:3], 0, v[20:21]
	v_lshl_add_u64 v[4:5], v[16:17], 0, v[4:5]
	v_mad_u64_u32 v[2:3], s[8:9], v4, v0, v[2:3]
	v_lshl_add_u64 v[10:11], s[14:15], 0, v[20:21]
	v_lshl_add_u64 v[12:13], s[68:69], 0, v[20:21]
	v_mov_b32_e32 v4, v3
	v_mad_u64_u32 v[0:1], s[8:9], v5, v0, v[4:5]
	v_cndmask_b32_e64 v5, v11, v13, s[4:5]
	v_cndmask_b32_e64 v4, v10, v12, s[4:5]
	v_mov_b32_e32 v3, v0
	v_lshl_add_u64 v[4:5], v[4:5], 0, v[6:7]
	global_load_dwordx4 v[0:3], v[2:3], off
	s_nop 0
	global_load_dwordx4 v[4:7], v[4:5], off
	s_and_saveexec_b64 s[4:5], s[6:7]
	s_xor_b64 s[4:5], exec, s[4:5]
	v_mov_b32_e32 v43, v21
	v_lshl_add_u64 v[10:11], v[36:37], 0, v[42:43]
	v_mad_u64_u32 v[8:9], s[6:7], v10, s29, v[12:13]
	v_mov_b32_e32 v10, v9
	v_mad_u64_u32 v[10:11], s[6:7], v11, s29, v[10:11]
	v_mov_b32_e32 v9, v10
	s_andn2_saveexec_b64 s[4:5], s[4:5]
	v_lshl_add_u64 v[8:9], v[10:11], 0, v[44:45]
	s_mov_b64 s[6:7], 0xa000
	v_lshl_add_u64 v[8:9], v[8:9], 0, s[6:7]
	s_or_b64 exec, exec, s[4:5]
	global_load_dwordx4 v[8:11], v[8:9], off
	v_mad_u64_u32 v[14:15], s[4:5], v115, s29, 0
	v_add_u32_e32 v15, v15, v112
	v_lshl_add_u64 v[14:15], v[12:13], 0, v[14:15]
	global_load_dwordx4 v[14:17], v[14:15], off
	v_or_b32_e32 v244, 16, v24
	v_or_b32_e32 v240, v36, v244
	v_mad_u64_u32 v[240:241], s[100:101], v240, s29, v[12:13]
	v_add_u32_e32 v241, v112, v241
	global_load_dwordx4 v[240:243], v[240:241], off
	v_add_u32_e32 v226, 13, v24
	v_or_b32_e32 v226, v36, v226
	v_add_u32_e32 v230, 14, v24
	v_mad_u64_u32 v[226:227], s[100:101], v226, s29, v[12:13]
	v_or_b32_e32 v230, v36, v230
	v_add_u32_e32 v234, 15, v24
	v_add_u32_e32 v227, v112, v227
	v_mad_u64_u32 v[230:231], s[100:101], v230, s29, v[12:13]
	v_or_b32_e32 v234, v36, v234
	global_load_dwordx4 v[226:229], v[226:227], off
	v_add_u32_e32 v231, v112, v231
	v_mad_u64_u32 v[234:235], s[100:101], v234, s29, v[12:13]
	global_load_dwordx4 v[230:233], v[230:231], off
	v_add_u32_e32 v235, v112, v235
	global_load_dwordx4 v[234:237], v[234:235], off
	s_waitcnt vmcnt(6)
	v_cndmask_b32_e64 v113, v4, 0, s[24:25]
	v_cndmask_b32_e64 v114, v5, 0, s[24:25]
	v_cndmask_b32_e64 v115, v6, 0, s[24:25]
	v_cndmask_b32_e64 v126, v7, 0, s[24:25]
	v_cndmask_b32_e64 v140, v0, 0, s[10:11]
	v_cndmask_b32_e64 v141, v1, 0, s[10:11]
	v_cndmask_b32_e64 v144, v2, 0, s[10:11]
	v_cndmask_b32_e64 v19, v3, 0, s[10:11]
	v_lshlrev_b32_e32 v18, 16, v19
	v_and_b32_e32 v19, 0xffff0000, v19
	v_bfe_u32 v20, v38, 6, 2
	s_waitcnt vmcnt(5)
	v_cndmask_b32_e64 v25, v8, 0, s[0:1]
	v_cndmask_b32_e64 v46, v9, 0, s[0:1]
	v_cndmask_b32_e64 v48, v10, 0, s[0:1]
	v_cndmask_b32_e64 v49, v11, 0, s[0:1]
	ds_read_b128 v[0:3], v108 offset:512
	ds_read_b128 v[4:7], v108 offset:528
	ds_read_b128 v[8:11], v108 offset:1536
	ds_read_b128 v[42:45], v108 offset:1552
	ds_read_b128 v[118:121], v108 offset:2560
	ds_read_b128 v[122:125], v108 offset:2576
	ds_read_b128 v[128:131], v108 offset:3584
	ds_read_b128 v[132:135], v108 offset:3600
	s_waitcnt lgkmcnt(6)
	v_pk_fma_f32 v[6:7], v[6:7], v[18:19], 0 op_sel_hi:[1,1,0]
	v_lshlrev_b32_e32 v18, 16, v126
	v_and_b32_e32 v19, 0xffff0000, v126
	s_waitcnt lgkmcnt(4)
	v_pk_fma_f32 v[6:7], v[44:45], v[18:19], v[6:7]
	v_lshlrev_b32_e32 v18, 16, v49
	v_and_b32_e32 v19, 0xffff0000, v49
	s_waitcnt lgkmcnt(2)
	v_pk_fma_f32 v[6:7], v[124:125], v[18:19], v[6:7]
	s_waitcnt vmcnt(4)
	v_lshlrev_b32_e32 v18, 16, v17
	v_and_b32_e32 v19, 0xffff0000, v17
	v_lshlrev_b32_e32 v44, 16, v144
	v_and_b32_e32 v45, 0xffff0000, v144
	s_waitcnt lgkmcnt(0)
	v_pk_fma_f32 v[6:7], v[134:135], v[18:19], v[6:7]
	v_pk_fma_f32 v[4:5], v[4:5], v[44:45], 0 op_sel_hi:[1,1,0]
	v_lshlrev_b32_e32 v44, 16, v115
	v_and_b32_e32 v45, 0xffff0000, v115
	v_mul_f32_e32 v17, 0xbfb8aa3b, v6
	v_pk_fma_f32 v[4:5], v[42:43], v[44:45], v[4:5]
	v_lshlrev_b32_e32 v42, 16, v48
	v_and_b32_e32 v43, 0xffff0000, v48
	v_exp_f32_e32 v17, v17
	v_pk_fma_f32 v[4:5], v[122:123], v[42:43], v[4:5]
	v_lshlrev_b32_e32 v42, 16, v16
	v_and_b32_e32 v43, 0xffff0000, v16
	v_pk_fma_f32 v[4:5], v[132:133], v[42:43], v[4:5]
	v_lshlrev_b32_e32 v42, 16, v141
	v_and_b32_e32 v43, 0xffff0000, v141
	v_pk_fma_f32 v[2:3], v[2:3], v[42:43], 0 op_sel_hi:[1,1,0]
	v_lshlrev_b32_e32 v42, 16, v114
	v_and_b32_e32 v43, 0xffff0000, v114
	v_pk_fma_f32 v[2:3], v[10:11], v[42:43], v[2:3]
	v_lshlrev_b32_e32 v42, 16, v140
	v_and_b32_e32 v43, 0xffff0000, v140
	v_add_f32_e32 v17, 1.0, v17
	v_pk_fma_f32 v[0:1], v[0:1], v[42:43], 0 op_sel_hi:[1,1,0]
	v_lshlrev_b32_e32 v42, 16, v113
	v_and_b32_e32 v43, 0xffff0000, v113
	v_rcp_f32_e32 v18, v17
	v_mul_f32_e32 v17, 0xbfb8aa3b, v7
	v_pk_fma_f32 v[0:1], v[8:9], v[42:43], v[0:1]
	v_lshlrev_b32_e32 v8, 16, v25
	v_and_b32_e32 v9, 0xffff0000, v25
	v_exp_f32_e32 v17, v17
	v_lshlrev_b32_e32 v10, 16, v46
	v_and_b32_e32 v11, 0xffff0000, v46
	v_pk_fma_f32 v[0:1], v[118:119], v[8:9], v[0:1]
	v_lshlrev_b32_e32 v8, 16, v14
	v_and_b32_e32 v9, 0xffff0000, v14
	v_pk_fma_f32 v[2:3], v[120:121], v[10:11], v[2:3]
	v_lshlrev_b32_e32 v10, 16, v15
	v_and_b32_e32 v11, 0xffff0000, v15
	v_pk_fma_f32 v[0:1], v[128:129], v[8:9], v[0:1]
	v_pk_fma_f32 v[2:3], v[130:131], v[10:11], v[2:3]
	v_mul_f32_e32 v8, 0xbfb8aa3b, v0
	v_mul_f32_e32 v9, 0xbfb8aa3b, v1
	v_mul_f32_e32 v10, 0xbfb8aa3b, v2
	v_mul_f32_e32 v11, 0xbfb8aa3b, v3
	v_exp_f32_e32 v8, v8
	v_exp_f32_e32 v9, v9
	v_add_f32_e32 v17, 1.0, v17
	v_exp_f32_e32 v10, v10
	v_exp_f32_e32 v11, v11
	v_rcp_f32_e32 v19, v17
	v_mul_f32_e32 v16, 0xbfb8aa3b, v4
	v_mul_f32_e32 v17, 0xbfb8aa3b, v5
	v_exp_f32_e32 v16, v16
	v_exp_f32_e32 v17, v17
	v_add_f32_e32 v8, 1.0, v8
	v_add_f32_e32 v9, 1.0, v9
	v_add_f32_e32 v10, 1.0, v10
	v_add_f32_e32 v11, 1.0, v11
	v_rcp_f32_e32 v8, v8
	v_rcp_f32_e32 v9, v9
	v_rcp_f32_e32 v10, v10
	v_rcp_f32_e32 v11, v11
	v_add_f32_e32 v16, 1.0, v16
	v_add_f32_e32 v17, 1.0, v17
	v_rcp_f32_e32 v16, v16
	v_rcp_f32_e32 v17, v17
	v_pk_mul_f32 v[0:1], v[0:1], v[8:9]
	v_pk_mul_f32 v[2:3], v[2:3], v[10:11]
	v_pk_mul_f32 v[8:9], v[0:1], v[0:1]
	v_pk_mul_f32 v[10:11], v[2:3], v[2:3]
	v_add_f32_e32 v8, v8, v9
	v_pk_mul_f32 v[4:5], v[4:5], v[16:17]
	v_add_f32_e32 v8, v10, v8
	v_pk_mul_f32 v[16:17], v[4:5], v[4:5]
	v_add_f32_e32 v8, v11, v8
	v_pk_mul_f32 v[6:7], v[6:7], v[18:19]
	v_add_f32_e32 v8, v16, v8
	v_pk_mul_f32 v[18:19], v[6:7], v[6:7]
	v_add_f32_e32 v8, v17, v8
	v_add_f32_e32 v8, v18, v8
	v_add_f32_e32 v8, v19, v8
	ds_bpermute_b32 v9, v23, v8
	v_or_b32_e32 v25, 16, v24
	s_waitcnt lgkmcnt(0)
	v_add_f32_e32 v8, v8, v9
	ds_bpermute_b32 v9, v109, v8
	s_waitcnt lgkmcnt(0)
	v_add_f32_e32 v8, v8, v9
	ds_bpermute_b32 v9, v110, v8
	s_waitcnt lgkmcnt(0)
	v_add_f32_e32 v8, v8, v9
	ds_bpermute_b32 v9, v111, v8
	s_waitcnt lgkmcnt(0)
	v_add_f32_e32 v8, v8, v9
	v_add_f32_e32 v8, 0x358637bd, v8
	v_cmp_gt_f32_e32 vcc, s70, v8
	v_mul_f32_e32 v9, 0x4b800000, v8
	s_nop 0
	v_cndmask_b32_e32 v8, v8, v9, vcc
	v_rsq_f32_e32 v8, v8
	s_nop 0
	v_mul_f32_e32 v9, 0x45800000, v8
	v_cndmask_b32_e32 v8, v8, v9, vcc
	v_pk_mul_f32 v[0:1], v[0:1], v[8:9] op_sel_hi:[1,0]
	v_pk_mul_f32 v[2:3], v[2:3], v[8:9] op_sel_hi:[1,0]
	v_pk_mul_f32 v[4:5], v[4:5], v[8:9] op_sel_hi:[1,0]
	v_pk_mul_f32 v[6:7], v[6:7], v[8:9] op_sel_hi:[1,0]
	v_cvt_pk_bf16_f32 v0, v0, v1
	v_cvt_pk_bf16_f32 v1, v2, v3
	v_cvt_pk_bf16_f32 v2, v4, v5
	v_cvt_pk_bf16_f32 v3, v6, v7
	ds_write_b128 v117, v[0:3] offset:21504
	v_add_u32_e32 v216, 31, v24
	v_or_b32_e32 v216, v36, v216
	v_mad_u64_u32 v[216:217], s[100:101], v216, s29, v[12:13]
	v_or3_b32 v222, v24, v36, 32
	v_add_u32_e32 v217, v112, v217
	v_mad_u64_u32 v[222:223], s[100:101], v222, s29, v[12:13]
	v_add_u32_e32 v223, v112, v223
	global_load_dwordx4 v[222:225], v[222:223], off
	v_add_u32_e32 v208, 29, v24
	v_or_b32_e32 v208, v36, v208
	v_add_u32_e32 v212, 30, v24
	v_mad_u64_u32 v[208:209], s[100:101], v208, s29, v[12:13]
	v_or_b32_e32 v212, v36, v212
	v_add_u32_e32 v209, v112, v209
	v_mad_u64_u32 v[212:213], s[100:101], v212, s29, v[12:13]
	global_load_dwordx4 v[208:211], v[208:209], off
	v_add_u32_e32 v213, v112, v213
	global_load_dwordx4 v[212:215], v[212:213], off
	s_nop 0
	global_load_dwordx4 v[216:219], v[216:217], off
	ds_read_b128 v[42:45], v108 offset:512
	ds_read_b128 v[118:121], v108 offset:528
	ds_read_b128 v[122:125], v108 offset:1536
	ds_read_b128 v[128:131], v108 offset:1552
	ds_read_b128 v[132:135], v108 offset:2560
	ds_read_b128 v[144:147], v108 offset:2576
	ds_read_b128 v[148:151], v108 offset:3584
	ds_read_b128 v[152:155], v108 offset:3600
	s_waitcnt vmcnt(6)
	v_lshlrev_b32_e32 v18, 16, v229
	v_and_b32_e32 v19, 0xffff0000, v229
	s_waitcnt lgkmcnt(6)
	v_pk_fma_f32 v[18:19], v[120:121], v[18:19], 0 op_sel_hi:[1,1,0]
	v_lshlrev_b32_e32 v114, 16, v228
	s_waitcnt vmcnt(5)
	v_lshlrev_b32_e32 v48, 16, v233
	v_and_b32_e32 v49, 0xffff0000, v233
	s_waitcnt lgkmcnt(4)
	v_pk_fma_f32 v[18:19], v[130:131], v[48:49], v[18:19]
	s_waitcnt vmcnt(4)
	v_lshlrev_b32_e32 v48, 16, v237
	v_and_b32_e32 v49, 0xffff0000, v237
	s_waitcnt lgkmcnt(2)
	v_pk_fma_f32 v[18:19], v[146:147], v[48:49], v[18:19]
	v_lshlrev_b32_e32 v48, 16, v243
	v_and_b32_e32 v49, 0xffff0000, v243
	s_waitcnt lgkmcnt(0)
	v_pk_fma_f32 v[18:19], v[154:155], v[48:49], v[18:19]
	v_and_b32_e32 v115, 0xffff0000, v228
	v_mul_f32_e32 v3, 0xbfb8aa3b, v18
	v_exp_f32_e32 v3, v3
	v_and_b32_e32 v7, 0xffff0000, v236
	v_and_b32_e32 v11, 0xffff0000, v227
	v_and_b32_e32 v17, 0xffff0000, v231
	v_add_f32_e32 v3, 1.0, v3
	v_rcp_f32_e32 v48, v3
	v_mul_f32_e32 v3, 0xbfb8aa3b, v19
	v_exp_f32_e32 v3, v3
	s_nop 0
	v_add_f32_e32 v3, 1.0, v3
	v_rcp_f32_e32 v49, v3
	v_pk_fma_f32 v[2:3], v[118:119], v[114:115], 0 op_sel_hi:[1,1,0]
	v_lshlrev_b32_e32 v114, 16, v232
	v_and_b32_e32 v115, 0xffff0000, v232
	v_pk_fma_f32 v[2:3], v[128:129], v[114:115], v[2:3]
	v_lshlrev_b32_e32 v6, 16, v236
	v_lshlrev_b32_e32 v10, 16, v227
	v_pk_fma_f32 v[2:3], v[144:145], v[6:7], v[2:3]
	v_lshlrev_b32_e32 v6, 16, v242
	v_and_b32_e32 v7, 0xffff0000, v242
	v_pk_fma_f32 v[10:11], v[44:45], v[10:11], 0 op_sel_hi:[1,1,0]
	v_lshlrev_b32_e32 v16, 16, v231
	v_pk_fma_f32 v[10:11], v[124:125], v[16:17], v[10:11]
	v_lshlrev_b32_e32 v16, 16, v235
	v_and_b32_e32 v17, 0xffff0000, v235
	v_pk_fma_f32 v[10:11], v[134:135], v[16:17], v[10:11]
	v_lshlrev_b32_e32 v16, 16, v241
	v_and_b32_e32 v17, 0xffff0000, v241
	v_pk_fma_f32 v[10:11], v[150:151], v[16:17], v[10:11]
	v_lshlrev_b32_e32 v44, 16, v226
	v_mul_f32_e32 v1, 0xbfb8aa3b, v10
	v_exp_f32_e32 v1, v1
	v_and_b32_e32 v45, 0xffff0000, v226
	v_and_b32_e32 v5, 0xffff0000, v234
	v_pk_fma_f32 v[2:3], v[152:153], v[6:7], v[2:3]
	v_add_f32_e32 v1, 1.0, v1
	v_rcp_f32_e32 v16, v1
	v_mul_f32_e32 v1, 0xbfb8aa3b, v11
	v_exp_f32_e32 v1, v1
	v_mul_f32_e32 v6, 0xbfb8aa3b, v2
	v_mul_f32_e32 v7, 0xbfb8aa3b, v3
	v_exp_f32_e32 v6, v6
	v_add_f32_e32 v1, 1.0, v1
	v_rcp_f32_e32 v17, v1
	v_pk_fma_f32 v[0:1], v[42:43], v[44:45], 0 op_sel_hi:[1,1,0]
	v_lshlrev_b32_e32 v42, 16, v230
	v_and_b32_e32 v43, 0xffff0000, v230
	v_pk_fma_f32 v[0:1], v[122:123], v[42:43], v[0:1]
	v_lshlrev_b32_e32 v4, 16, v234
	v_pk_fma_f32 v[0:1], v[132:133], v[4:5], v[0:1]
	v_lshlrev_b32_e32 v4, 16, v240
	v_and_b32_e32 v5, 0xffff0000, v240
	v_pk_fma_f32 v[0:1], v[148:149], v[4:5], v[0:1]
	v_exp_f32_e32 v7, v7
	v_mul_f32_e32 v4, 0xbfb8aa3b, v0
	v_mul_f32_e32 v5, 0xbfb8aa3b, v1
	v_exp_f32_e32 v4, v4
	v_exp_f32_e32 v5, v5
	v_add_f32_e32 v6, 1.0, v6
	v_add_f32_e32 v7, 1.0, v7
	v_add_f32_e32 v4, 1.0, v4
	v_add_f32_e32 v5, 1.0, v5
	v_rcp_f32_e32 v4, v4
	v_rcp_f32_e32 v5, v5
	v_rcp_f32_e32 v6, v6
	v_rcp_f32_e32 v7, v7
	v_pk_mul_f32 v[10:11], v[10:11], v[16:17]
	v_pk_mul_f32 v[0:1], v[0:1], v[4:5]
	v_pk_mul_f32 v[16:17], v[10:11], v[10:11]
	v_pk_mul_f32 v[4:5], v[0:1], v[0:1]
	v_pk_mul_f32 v[2:3], v[2:3], v[6:7]
	v_add_f32_e32 v4, v4, v5
	v_add_f32_e32 v4, v16, v4
	v_pk_mul_f32 v[6:7], v[2:3], v[2:3]
	v_add_f32_e32 v4, v17, v4
	v_pk_mul_f32 v[18:19], v[18:19], v[48:49]
	v_add_f32_e32 v4, v6, v4
	v_pk_mul_f32 v[48:49], v[18:19], v[18:19]
	v_add_f32_e32 v4, v7, v4
	v_add_f32_e32 v4, v48, v4
	v_add_f32_e32 v4, v49, v4
	ds_bpermute_b32 v5, v23, v4
	s_waitcnt lgkmcnt(0)
	v_add_f32_e32 v4, v4, v5
	ds_bpermute_b32 v5, v109, v4
	s_waitcnt lgkmcnt(0)
	v_add_f32_e32 v4, v4, v5
	ds_bpermute_b32 v5, v110, v4
	s_waitcnt lgkmcnt(0)
	v_add_f32_e32 v4, v4, v5
	ds_bpermute_b32 v5, v111, v4
	s_waitcnt lgkmcnt(0)
	v_add_f32_e32 v4, v4, v5
	v_add_f32_e32 v4, 0x358637bd, v4
	v_cmp_gt_f32_e32 vcc, s70, v4
	v_mul_f32_e32 v5, 0x4b800000, v4
	s_nop 0
	v_cndmask_b32_e32 v4, v4, v5, vcc
	v_rsq_f32_e32 v4, v4
	s_nop 0
	v_mul_f32_e32 v5, 0x45800000, v4
	v_cndmask_b32_e32 v4, v4, v5, vcc
	v_pk_mul_f32 v[0:1], v[0:1], v[4:5] op_sel_hi:[1,0]
	v_pk_mul_f32 v[6:7], v[10:11], v[4:5] op_sel_hi:[1,0]
	v_pk_mul_f32 v[2:3], v[2:3], v[4:5] op_sel_hi:[1,0]
	v_pk_mul_f32 v[4:5], v[18:19], v[4:5] op_sel_hi:[1,0]
	v_cvt_pk_bf16_f32 v2, v2, v3
	v_cvt_pk_bf16_f32 v3, v4, v5
	v_mul_u32_u24_e32 v4, 0x110, v25
	v_cvt_pk_bf16_f32 v0, v0, v1
	v_cvt_pk_bf16_f32 v1, v6, v7
	v_add3_u32 v25, v196, v4, v26
	ds_write_b128 v25, v[0:3] offset:21504
	s_waitcnt vmcnt(2)
	v_lshlrev_b32_e32 v18, 16, v211
	v_bfe_u32 v234, v38, 4, 4
	v_add_u32_e32 v226, 45, v234
	v_or_b32_e32 v226, v36, v226
	v_add_u32_e32 v230, 46, v234
	v_or_b32_e32 v244, 48, v234
	v_mad_u64_u32 v[226:227], s[100:101], v226, s29, v[12:13]
	v_or_b32_e32 v230, v36, v230
	v_add_u32_e32 v234, 47, v234
	v_add_u32_e32 v227, v112, v227
	v_mad_u64_u32 v[230:231], s[100:101], v230, s29, v[12:13]
	v_or_b32_e32 v234, v36, v234
	global_load_dwordx4 v[226:229], v[226:227], off
	v_add_u32_e32 v231, v112, v231
	v_mad_u64_u32 v[234:235], s[100:101], v234, s29, v[12:13]
	v_or_b32_e32 v240, v36, v244
	global_load_dwordx4 v[230:233], v[230:231], off
	v_add_u32_e32 v235, v112, v235
	v_mad_u64_u32 v[238:239], s[100:101], v240, s29, v[12:13]
	global_load_dwordx4 v[234:237], v[234:235], off
	v_add_u32_e32 v239, v112, v239
	global_load_dwordx4 v[238:241], v[238:239], off
	ds_read_b128 v[42:45], v108 offset:512
	ds_read_b128 v[118:121], v108 offset:528
	ds_read_b128 v[122:125], v108 offset:1536
	ds_read_b128 v[128:131], v108 offset:1552
	ds_read_b128 v[132:135], v108 offset:2560
	ds_read_b128 v[144:147], v108 offset:2576
	ds_read_b128 v[148:151], v108 offset:3584
	ds_read_b128 v[152:155], v108 offset:3600
	v_and_b32_e32 v19, 0xffff0000, v211
	s_waitcnt lgkmcnt(6)
	v_pk_fma_f32 v[18:19], v[120:121], v[18:19], 0 op_sel_hi:[1,1,0]
	s_waitcnt vmcnt(5)
	v_lshlrev_b32_e32 v48, 16, v215
	v_and_b32_e32 v49, 0xffff0000, v215
	s_waitcnt lgkmcnt(4)
	v_pk_fma_f32 v[18:19], v[130:131], v[48:49], v[18:19]
	v_lshlrev_b32_e32 v114, 16, v210
	v_and_b32_e32 v115, 0xffff0000, v210
	s_waitcnt vmcnt(4)
	v_lshlrev_b32_e32 v48, 16, v219
	v_and_b32_e32 v49, 0xffff0000, v219
	s_waitcnt lgkmcnt(2)
	v_pk_fma_f32 v[18:19], v[146:147], v[48:49], v[18:19]
	v_lshlrev_b32_e32 v48, 16, v225
	v_and_b32_e32 v49, 0xffff0000, v225
	s_waitcnt lgkmcnt(0)
	v_pk_fma_f32 v[18:19], v[154:155], v[48:49], v[18:19]
	v_and_b32_e32 v7, 0xffff0000, v218
	v_mul_f32_e32 v3, 0xbfb8aa3b, v18
	v_exp_f32_e32 v3, v3
	v_and_b32_e32 v11, 0xffff0000, v209
	v_and_b32_e32 v17, 0xffff0000, v213
	v_add_f32_e32 v3, 1.0, v3
	v_rcp_f32_e32 v48, v3
	v_mul_f32_e32 v3, 0xbfb8aa3b, v19
	v_exp_f32_e32 v3, v3
	s_nop 0
	v_add_f32_e32 v3, 1.0, v3
	v_rcp_f32_e32 v49, v3
	v_pk_fma_f32 v[2:3], v[118:119], v[114:115], 0 op_sel_hi:[1,1,0]
	v_lshlrev_b32_e32 v114, 16, v214
	v_and_b32_e32 v115, 0xffff0000, v214
	v_pk_fma_f32 v[2:3], v[128:129], v[114:115], v[2:3]
	v_lshlrev_b32_e32 v6, 16, v218
	v_lshlrev_b32_e32 v10, 16, v209
	v_pk_fma_f32 v[2:3], v[144:145], v[6:7], v[2:3]
	v_lshlrev_b32_e32 v6, 16, v224
	v_and_b32_e32 v7, 0xffff0000, v224
	v_pk_fma_f32 v[10:11], v[44:45], v[10:11], 0 op_sel_hi:[1,1,0]
	v_lshlrev_b32_e32 v16, 16, v213
	v_pk_fma_f32 v[10:11], v[124:125], v[16:17], v[10:11]
	v_lshlrev_b32_e32 v16, 16, v217
	v_and_b32_e32 v17, 0xffff0000, v217
	v_pk_fma_f32 v[10:11], v[134:135], v[16:17], v[10:11]
	v_lshlrev_b32_e32 v16, 16, v223
	v_and_b32_e32 v17, 0xffff0000, v223
	v_pk_fma_f32 v[10:11], v[150:151], v[16:17], v[10:11]
	v_lshlrev_b32_e32 v44, 16, v208
	v_mul_f32_e32 v1, 0xbfb8aa3b, v10
	v_exp_f32_e32 v1, v1
	v_and_b32_e32 v45, 0xffff0000, v208
	v_and_b32_e32 v5, 0xffff0000, v216
	v_pk_fma_f32 v[2:3], v[152:153], v[6:7], v[2:3]
	v_add_f32_e32 v1, 1.0, v1
	v_rcp_f32_e32 v16, v1
	v_mul_f32_e32 v1, 0xbfb8aa3b, v11
	v_exp_f32_e32 v1, v1
	v_mul_f32_e32 v6, 0xbfb8aa3b, v2
	v_mul_f32_e32 v7, 0xbfb8aa3b, v3
	v_exp_f32_e32 v6, v6
	v_add_f32_e32 v1, 1.0, v1
	v_rcp_f32_e32 v17, v1
	v_pk_fma_f32 v[0:1], v[42:43], v[44:45], 0 op_sel_hi:[1,1,0]
	v_lshlrev_b32_e32 v42, 16, v212
	v_and_b32_e32 v43, 0xffff0000, v212
	v_pk_fma_f32 v[0:1], v[122:123], v[42:43], v[0:1]
	v_lshlrev_b32_e32 v4, 16, v216
	v_pk_fma_f32 v[0:1], v[132:133], v[4:5], v[0:1]
	v_lshlrev_b32_e32 v4, 16, v222
	v_and_b32_e32 v5, 0xffff0000, v222
	v_pk_fma_f32 v[0:1], v[148:149], v[4:5], v[0:1]
	v_exp_f32_e32 v7, v7
	v_mul_f32_e32 v4, 0xbfb8aa3b, v0
	v_mul_f32_e32 v5, 0xbfb8aa3b, v1
	v_exp_f32_e32 v4, v4
	v_exp_f32_e32 v5, v5
	v_add_f32_e32 v6, 1.0, v6
	v_add_f32_e32 v7, 1.0, v7
	v_add_f32_e32 v4, 1.0, v4
	v_add_f32_e32 v5, 1.0, v5
	v_rcp_f32_e32 v4, v4
	v_rcp_f32_e32 v5, v5
	v_rcp_f32_e32 v6, v6
	v_rcp_f32_e32 v7, v7
	v_pk_mul_f32 v[10:11], v[10:11], v[16:17]
	v_pk_mul_f32 v[0:1], v[0:1], v[4:5]
	v_pk_mul_f32 v[16:17], v[10:11], v[10:11]
	v_pk_mul_f32 v[4:5], v[0:1], v[0:1]
	v_pk_mul_f32 v[2:3], v[2:3], v[6:7]
	v_add_f32_e32 v4, v4, v5
	v_add_f32_e32 v4, v16, v4
	v_pk_mul_f32 v[6:7], v[2:3], v[2:3]
	v_add_f32_e32 v4, v17, v4
	v_pk_mul_f32 v[18:19], v[18:19], v[48:49]
	v_add_f32_e32 v4, v6, v4
	v_pk_mul_f32 v[48:49], v[18:19], v[18:19]
	v_add_f32_e32 v4, v7, v4
	v_add_f32_e32 v4, v48, v4
	v_add_f32_e32 v4, v49, v4
	ds_bpermute_b32 v5, v23, v4
	v_bfe_u32 v8, v38, 4, 4
	s_waitcnt lgkmcnt(0)
	v_add_f32_e32 v4, v4, v5
	ds_bpermute_b32 v5, v109, v4
	s_waitcnt lgkmcnt(0)
	v_add_f32_e32 v4, v4, v5
	ds_bpermute_b32 v5, v110, v4
	s_waitcnt lgkmcnt(0)
	v_add_f32_e32 v4, v4, v5
	ds_bpermute_b32 v5, v111, v4
	s_waitcnt lgkmcnt(0)
	v_add_f32_e32 v4, v4, v5
	v_add_f32_e32 v4, 0x358637bd, v4
	v_cmp_gt_f32_e32 vcc, s70, v4
	v_mul_f32_e32 v5, 0x4b800000, v4
	s_nop 0
	v_cndmask_b32_e32 v4, v4, v5, vcc
	v_rsq_f32_e32 v4, v4
	s_nop 0
	v_mul_f32_e32 v5, 0x45800000, v4
	v_cndmask_b32_e32 v4, v4, v5, vcc
	v_pk_mul_f32 v[0:1], v[0:1], v[4:5] op_sel_hi:[1,0]
	v_pk_mul_f32 v[6:7], v[10:11], v[4:5] op_sel_hi:[1,0]
	v_pk_mul_f32 v[2:3], v[2:3], v[4:5] op_sel_hi:[1,0]
	v_pk_mul_f32 v[4:5], v[18:19], v[4:5] op_sel_hi:[1,0]
	v_cvt_pk_bf16_f32 v0, v0, v1
	v_cvt_pk_bf16_f32 v1, v6, v7
	v_cvt_pk_bf16_f32 v2, v2, v3
	v_cvt_pk_bf16_f32 v3, v4, v5
	ds_write_b128 v25, v[0:3] offset:25856
	v_or_b32_e32 v25, 48, v8
	ds_read_b128 v[16:19], v108 offset:512
	ds_read_b128 v[42:45], v108 offset:528
	ds_read_b128 v[112:115], v108 offset:1536
	ds_read_b128 v[118:121], v108 offset:1552
	ds_read_b128 v[122:125], v108 offset:2560
	ds_read_b128 v[128:131], v108 offset:2576
	ds_read_b128 v[132:135], v108 offset:3584
	ds_read_b128 v[144:147], v108 offset:3600
	s_waitcnt vmcnt(3)
	v_lshlrev_b32_e32 v48, 16, v229
	v_and_b32_e32 v49, 0xffff0000, v229
	s_waitcnt lgkmcnt(6)
	v_pk_fma_f32 v[44:45], v[44:45], v[48:49], 0 op_sel_hi:[1,1,0]
	s_waitcnt vmcnt(2)
	v_lshlrev_b32_e32 v48, 16, v233
	v_and_b32_e32 v49, 0xffff0000, v233
	s_waitcnt lgkmcnt(4)
	v_pk_fma_f32 v[44:45], v[120:121], v[48:49], v[44:45]
	v_lshlrev_b32_e32 v120, 16, v228
	s_waitcnt vmcnt(1)
	v_lshlrev_b32_e32 v48, 16, v237
	v_and_b32_e32 v49, 0xffff0000, v237
	s_waitcnt lgkmcnt(2)
	v_pk_fma_f32 v[44:45], v[130:131], v[48:49], v[44:45]
	s_waitcnt vmcnt(0)
	v_lshlrev_b32_e32 v48, 16, v241
	v_and_b32_e32 v49, 0xffff0000, v241
	s_waitcnt lgkmcnt(0)
	v_pk_fma_f32 v[44:45], v[146:147], v[48:49], v[44:45]
	v_and_b32_e32 v121, 0xffff0000, v228
	v_mul_f32_e32 v3, 0xbfb8aa3b, v44
	v_exp_f32_e32 v3, v3
	v_and_b32_e32 v7, 0xffff0000, v236
	v_and_b32_e32 v11, 0xffff0000, v227
	v_and_b32_e32 v15, 0xffff0000, v231
	v_add_f32_e32 v3, 1.0, v3
	v_rcp_f32_e32 v48, v3
	v_mul_f32_e32 v3, 0xbfb8aa3b, v45
	v_exp_f32_e32 v3, v3
	s_nop 0
	v_add_f32_e32 v3, 1.0, v3
	v_rcp_f32_e32 v49, v3
	v_pk_fma_f32 v[2:3], v[42:43], v[120:121], 0 op_sel_hi:[1,1,0]
	v_lshlrev_b32_e32 v42, 16, v232
	v_and_b32_e32 v43, 0xffff0000, v232
	v_pk_fma_f32 v[2:3], v[118:119], v[42:43], v[2:3]
	v_lshlrev_b32_e32 v6, 16, v236
	v_lshlrev_b32_e32 v10, 16, v227
	v_pk_fma_f32 v[2:3], v[128:129], v[6:7], v[2:3]
	v_lshlrev_b32_e32 v6, 16, v240
	v_and_b32_e32 v7, 0xffff0000, v240
	v_pk_fma_f32 v[10:11], v[18:19], v[10:11], 0 op_sel_hi:[1,1,0]
	v_lshlrev_b32_e32 v14, 16, v231
	v_pk_fma_f32 v[10:11], v[114:115], v[14:15], v[10:11]
	v_lshlrev_b32_e32 v14, 16, v235
	v_and_b32_e32 v15, 0xffff0000, v235
	v_pk_fma_f32 v[10:11], v[124:125], v[14:15], v[10:11]
	v_lshlrev_b32_e32 v14, 16, v239
	v_and_b32_e32 v15, 0xffff0000, v239
	v_pk_fma_f32 v[10:11], v[134:135], v[14:15], v[10:11]
	v_lshlrev_b32_e32 v18, 16, v226
	v_mul_f32_e32 v1, 0xbfb8aa3b, v10
	v_exp_f32_e32 v1, v1
	v_and_b32_e32 v19, 0xffff0000, v226
	v_and_b32_e32 v5, 0xffff0000, v234
	v_pk_fma_f32 v[2:3], v[144:145], v[6:7], v[2:3]
	v_add_f32_e32 v1, 1.0, v1
	v_rcp_f32_e32 v14, v1
	v_mul_f32_e32 v1, 0xbfb8aa3b, v11
	v_exp_f32_e32 v1, v1
	v_mul_f32_e32 v6, 0xbfb8aa3b, v2
	v_mul_f32_e32 v7, 0xbfb8aa3b, v3
	v_exp_f32_e32 v6, v6
	v_add_f32_e32 v1, 1.0, v1
	v_rcp_f32_e32 v15, v1
	v_pk_fma_f32 v[0:1], v[16:17], v[18:19], 0 op_sel_hi:[1,1,0]
	v_lshlrev_b32_e32 v16, 16, v230
	v_and_b32_e32 v17, 0xffff0000, v230
	v_pk_fma_f32 v[0:1], v[112:113], v[16:17], v[0:1]
	v_lshlrev_b32_e32 v4, 16, v234
	v_pk_fma_f32 v[0:1], v[122:123], v[4:5], v[0:1]
	v_lshlrev_b32_e32 v4, 16, v238
	v_and_b32_e32 v5, 0xffff0000, v238
	v_pk_fma_f32 v[0:1], v[132:133], v[4:5], v[0:1]
	v_exp_f32_e32 v7, v7
	v_mul_f32_e32 v4, 0xbfb8aa3b, v0
	v_mul_f32_e32 v5, 0xbfb8aa3b, v1
	v_exp_f32_e32 v4, v4
	v_exp_f32_e32 v5, v5
	v_add_f32_e32 v6, 1.0, v6
	v_add_f32_e32 v7, 1.0, v7
	v_add_f32_e32 v4, 1.0, v4
	v_add_f32_e32 v5, 1.0, v5
	v_rcp_f32_e32 v4, v4
	v_rcp_f32_e32 v5, v5
	v_rcp_f32_e32 v6, v6
	v_rcp_f32_e32 v7, v7
	v_pk_mul_f32 v[10:11], v[10:11], v[14:15]
	v_pk_mul_f32 v[0:1], v[0:1], v[4:5]
	v_pk_mul_f32 v[14:15], v[10:11], v[10:11]
	v_pk_mul_f32 v[4:5], v[0:1], v[0:1]
	v_pk_mul_f32 v[2:3], v[2:3], v[6:7]
	v_add_f32_e32 v4, v4, v5
	v_add_f32_e32 v4, v14, v4
	v_pk_mul_f32 v[6:7], v[2:3], v[2:3]
	v_add_f32_e32 v4, v15, v4
	v_pk_mul_f32 v[44:45], v[44:45], v[48:49]
	v_add_f32_e32 v4, v6, v4
	v_pk_mul_f32 v[48:49], v[44:45], v[44:45]
	v_add_f32_e32 v4, v7, v4
	v_add_f32_e32 v4, v48, v4
	v_add_f32_e32 v4, v49, v4
	ds_bpermute_b32 v5, v23, v4
	v_lshlrev_b32_e32 v16, 5, v40
	s_waitcnt lgkmcnt(0)
	v_add_f32_e32 v4, v4, v5
	ds_bpermute_b32 v5, v109, v4
	s_waitcnt lgkmcnt(0)
	v_add_f32_e32 v4, v4, v5
	ds_bpermute_b32 v5, v110, v4
	s_waitcnt lgkmcnt(0)
	v_add_f32_e32 v4, v4, v5
	ds_bpermute_b32 v5, v111, v4
	s_waitcnt lgkmcnt(0)
	v_add_f32_e32 v4, v4, v5
	v_add_f32_e32 v4, 0x358637bd, v4
	v_cmp_gt_f32_e32 vcc, s70, v4
	v_mul_f32_e32 v5, 0x4b800000, v4
	s_nop 0
	v_cndmask_b32_e32 v4, v4, v5, vcc
	v_rsq_f32_e32 v4, v4
	s_nop 0
	v_mul_f32_e32 v5, 0x45800000, v4
	v_cndmask_b32_e32 v4, v4, v5, vcc
	v_pk_mul_f32 v[0:1], v[0:1], v[4:5] op_sel_hi:[1,0]
	v_pk_mul_f32 v[6:7], v[10:11], v[4:5] op_sel_hi:[1,0]
	v_pk_mul_f32 v[2:3], v[2:3], v[4:5] op_sel_hi:[1,0]
	v_pk_mul_f32 v[4:5], v[44:45], v[4:5] op_sel_hi:[1,0]
	v_cvt_pk_bf16_f32 v2, v2, v3
	v_cvt_pk_bf16_f32 v3, v4, v5
	v_mul_u32_u24_e32 v4, 0x110, v25
	v_cvt_pk_bf16_f32 v0, v0, v1
	v_cvt_pk_bf16_f32 v1, v6, v7
	v_add3_u32 v4, v196, v4, v26
	ds_write_b128 v4, v[0:3] offset:21504
	v_cmp_lt_u32_e32 vcc, 1, v20
	v_add_u32_e32 v2, 0x5400, v196
	s_and_saveexec_b64 s[0:1], vcc
	s_xor_b64 s[0:1], exec, s[0:1]
	v_add_u32_e32 v2, 0x1000, v196
	v_lshlrev_b32_e32 v16, 5, v40
	s_or_saveexec_b64 s[0:1], s[0:1]
	v_mov_b32_e32 v23, v37
	v_and_b32_e32 v14, 63, v38
	v_add_u32_e32 v15, 0x11800, v196
	v_add_u32_e32 v12, 0x11c00, v196
	v_add_u32_e32 v13, 0x11a00, v196
	v_mov_b32_e32 v0, 0xc800
	s_xor_b64 exec, exec, s[0:1]
	s_cbranch_execz .LBB0_293
	v_or_b32_e32 v3, v107, v20
	v_lshlrev_b32_e32 v20, 16, v3
	v_lshl_add_u64 v[0:1], s[16:17], 0, v[20:21]
	v_lshlrev_b64 v[4:5], 2, v[22:23]
	v_lshl_add_u64 v[6:7], v[0:1], 0, v[4:5]
	v_lshl_add_u64 v[4:5], s[16:17], 0, v[4:5]
	v_lshlrev_b32_e32 v0, 2, v14
	v_mov_b32_e32 v1, v21
	v_lshl_add_u64 v[4:5], v[4:5], 0, v[20:21]
	v_lshl_add_u64 v[4:5], v[4:5], 0, v[0:1]
	v_add_co_u32_e32 v4, vcc, 0x200000, v4
	v_lshl_add_u64 v[6:7], v[6:7], 0, v[0:1]
	s_nop 0
	v_addc_co_u32_e32 v5, vcc, 0, v5, vcc
	v_readlane_b32 s36, v250, 19
	s_waitcnt vmcnt(0)
	v_mov_b32_e32 v7, v246
	v_readlane_b32 s37, v250, 20
	v_mov_b32_e32 v4, v247
	v_lshlrev_b32_e32 v6, 2, v3
	s_mov_b32 s2, 0xbfb8aa3b
	v_readlane_b32 s38, v250, 21
	v_readlane_b32 s39, v250, 22
	v_mov_b32_e32 v5, v248
	v_readlane_b32 s40, v250, 23
	v_readlane_b32 s41, v250, 24
	v_readlane_b32 s42, v250, 25
	v_readlane_b32 s43, v250, 26
	v_readlane_b32 s44, v250, 27
	v_readlane_b32 s45, v250, 28
	v_readlane_b32 s46, v250, 29
	v_readlane_b32 s47, v250, 30
	v_readlane_b32 s48, v250, 31
	v_readlane_b32 s49, v250, 32
	v_readlane_b32 s50, v250, 33
	v_readlane_b32 s51, v250, 34
	v_readlane_b32 s36, v250, 3
	v_readlane_b32 s50, v250, 17
	v_readlane_b32 s51, v250, 18
	v_readlane_b32 s4, v250, 41
	v_readlane_b32 s5, v250, 42
	v_readlane_b32 s37, v250, 4
	v_readlane_b32 s38, v250, 5
	v_readlane_b32 s39, v250, 6
	v_mov_b32_e32 v6, v249
	v_readlane_b32 s40, v250, 7
	v_readlane_b32 s41, v250, 8
	v_readlane_b32 s42, v250, 9
	v_readlane_b32 s43, v250, 10
	v_readlane_b32 s44, v250, 11
	v_readlane_b32 s45, v250, 12
	v_readlane_b32 s46, v250, 13
	v_readlane_b32 s47, v250, 14
	v_readlane_b32 s48, v250, 15
	v_readlane_b32 s49, v250, 16
	s_waitcnt vmcnt(2)
	v_mul_f32_e32 v4, 0xbfb8aa3b, v4
	v_exp_f32_e32 v4, v4
	s_waitcnt vmcnt(1)
	v_add_f32_e32 v5, v7, v5
	v_mul_f32_e64 v8, |v5|, s2
	v_fma_f32 v9, |v5|, s2, -v8
	s_mov_b32 s2, 0xb2a5705f
	v_rndne_f32_e32 v10, v8
	v_fma_f32 v9, |v5|, s2, v9
	v_sub_f32_e32 v8, v8, v10
	v_add_f32_e32 v8, v8, v9
	v_exp_f32_e32 v8, v8
	v_cvt_i32_f32_e32 v9, v10
	s_mov_b32 s2, 0x42ce8ed0
	v_cmp_ngt_f32_e64 vcc, |v5|, s2
	s_mov_b32 s2, 0xc2b17218
	v_ldexp_f32 v8, v8, v9
	v_cndmask_b32_e32 v8, 0, v8, vcc
	v_cmp_nlt_f32_e64 vcc, |v5|, s2
	v_max_f32_e32 v7, 0, v5
	s_mov_b32 s2, 0x3f2aaaab
	v_cndmask_b32_e32 v5, v193, v8, vcc
	v_add_f32_e32 v10, 1.0, v5
	v_add_f32_e32 v8, -1.0, v10
	v_sub_f32_e32 v9, v8, v10
	v_add_f32_e32 v9, 1.0, v9
	v_sub_f32_e32 v8, v5, v8
	v_add_f32_e32 v11, v8, v9
	v_frexp_mant_f32_e32 v8, v10
	v_cmp_gt_f32_e32 vcc, s2, v8
	v_cvt_f64_f32_e32 v[8:9], v10
	v_frexp_exp_i32_f64_e32 v8, v[8:9]
	v_subbrev_co_u32_e32 v8, vcc, 0, v8, vcc
	v_sub_u32_e32 v9, 0, v8
	v_ldexp_f32 v10, v10, v9
	v_ldexp_f32 v9, v11, v9
	v_add_f32_e32 v11, -1.0, v10
	v_add_f32_e32 v17, 1.0, v11
	v_sub_f32_e32 v17, v10, v17
	v_add_f32_e32 v17, v9, v17
	v_add_f32_e32 v18, v11, v17
	v_sub_f32_e32 v11, v11, v18
	v_add_f32_e32 v11, v17, v11
	v_add_f32_e32 v17, 1.0, v10
	v_add_f32_e32 v19, -1.0, v17
	v_sub_f32_e32 v10, v10, v19
	v_add_f32_e32 v9, v9, v10
	v_add_f32_e32 v10, v17, v9
	v_sub_f32_e32 v17, v17, v10
	v_add_f32_e32 v9, v9, v17
	v_rcp_f32_e32 v17, v10
	v_cvt_f32_i32_e32 v8, v8
	s_mov_b32 s2, 0x3f317218
	v_add_f32_e32 v4, 1.0, v4
	v_mul_f32_e32 v19, v18, v17
	v_mul_f32_e32 v20, v10, v19
	v_fma_f32 v25, v19, v10, -v20
	v_fmac_f32_e32 v25, v19, v9
	v_add_f32_e32 v36, v20, v25
	v_sub_f32_e32 v40, v18, v36
	v_sub_f32_e32 v18, v18, v40
	v_sub_f32_e32 v20, v36, v20
	v_sub_f32_e32 v18, v18, v36
	v_add_f32_e32 v11, v11, v18
	v_sub_f32_e32 v18, v20, v25
	v_add_f32_e32 v11, v18, v11
	v_add_f32_e32 v18, v40, v11
	v_mul_f32_e32 v20, v17, v18
	v_mul_f32_e32 v25, v10, v20
	v_fma_f32 v10, v20, v10, -v25
	v_fmac_f32_e32 v10, v20, v9
	v_sub_f32_e32 v9, v40, v18
	v_add_f32_e32 v9, v11, v9
	v_add_f32_e32 v11, v25, v10
	v_sub_f32_e32 v36, v18, v11
	v_sub_f32_e32 v18, v18, v36
	v_sub_f32_e32 v25, v11, v25
	v_sub_f32_e32 v11, v18, v11
	v_add_f32_e32 v9, v9, v11
	v_sub_f32_e32 v10, v25, v10
	v_add_f32_e32 v9, v10, v9
	v_add_f32_e32 v10, v19, v20
	v_add_f32_e32 v9, v36, v9
	v_sub_f32_e32 v11, v10, v19
	v_mul_f32_e32 v9, v17, v9
	v_sub_f32_e32 v11, v20, v11
	v_add_f32_e32 v9, v11, v9
	v_mul_f32_e32 v19, 0x3f317218, v8
	v_add_f32_e32 v11, v10, v9
	v_fma_f32 v20, v8, s2, -v19
	v_mul_f32_e32 v17, v11, v11
	v_fmac_f32_e32 v20, 0xb102e308, v8
	v_sub_f32_e32 v8, v11, v10
	v_fmamk_f32 v18, v17, 0x3e9b6dac, v188
	v_sub_f32_e32 v8, v9, v8
	v_add_f32_e32 v9, v19, v20
	v_fmaak_f32 v18, v17, v18, 0x3f2aaada
	v_sub_f32_e32 v10, v9, v19
	v_ldexp_f32 v19, v11, 1
	v_mul_f32_e32 v11, v11, v17
	v_mul_f32_e32 v11, v11, v18
	v_add_f32_e32 v17, v19, v11
	v_sub_f32_e32 v18, v17, v19
	v_ldexp_f32 v8, v8, 1
	v_sub_f32_e32 v11, v11, v18
	v_add_f32_e32 v8, v8, v11
	v_add_f32_e32 v11, v17, v8
	v_sub_f32_e32 v17, v11, v17
	v_sub_f32_e32 v8, v8, v17
	v_add_f32_e32 v17, v9, v11
	v_sub_f32_e32 v18, v17, v9
	v_sub_f32_e32 v19, v17, v18
	v_sub_f32_e32 v10, v20, v10
	v_sub_f32_e32 v9, v9, v19
	v_sub_f32_e32 v11, v11, v18
	v_add_f32_e32 v9, v11, v9
	v_add_f32_e32 v11, v10, v8
	v_sub_f32_e32 v18, v11, v10
	v_sub_f32_e32 v19, v11, v18
	v_sub_f32_e32 v10, v10, v19
	v_sub_f32_e32 v8, v8, v18
	v_add_f32_e32 v9, v11, v9
	v_add_f32_e32 v8, v8, v10
	v_add_f32_e32 v10, v17, v9
	v_sub_f32_e32 v11, v10, v17
	v_sub_f32_e32 v9, v9, v11
	v_add_f32_e32 v8, v8, v9
	s_mov_b32 s2, 0x7f800000
	v_add_f32_e32 v8, v10, v8
	v_cmp_neq_f32_e32 vcc, s2, v5
	s_mov_b32 s2, 0x33800000
	v_rcp_f32_e32 v4, v4
	v_cndmask_b32_e32 v8, v193, v8, vcc
	v_cmp_lt_f32_e64 vcc, |v5|, s2
	s_mov_b32 s2, 0x3fb8aa3b
	v_lshlrev_b32_e32 v20, 2, v39
	v_cndmask_b32_e32 v5, v8, v5, vcc
	v_add_f32_e32 v5, v7, v5
	s_waitcnt vmcnt(0)
	v_mul_f32_e32 v7, 0x3fb8aa3b, v6
	v_fma_f32 v8, v6, s2, -v7
	v_rndne_f32_e32 v9, v7
	v_fmac_f32_e32 v8, 0x32a5705f, v6
	v_sub_f32_e32 v7, v7, v9
	v_add_f32_e32 v7, v7, v8
	v_exp_f32_e32 v7, v7
	v_cvt_i32_f32_e32 v8, v9
	s_mov_b32 s2, 0xc2ce8ed0
	v_cmp_ngt_f32_e32 vcc, s2, v6
	s_mov_b32 s2, 0x42b17218
	v_ldexp_f32 v7, v7, v8
	v_cndmask_b32_e32 v7, 0, v7, vcc
	v_cmp_nlt_f32_e32 vcc, s2, v6
	v_add_u32_e32 v8, -1, v191
	s_nop 0
	v_cndmask_b32_e32 v7, v193, v7, vcc
	v_cmp_lt_i32_e32 vcc, v8, v47
	v_mul_f32_e64 v6, v5, -v7
	s_nop 0
	v_cndmask_b32_e32 v8, v8, v191, vcc
	v_lshlrev_b32_e32 v8, 2, v8
	ds_bpermute_b32 v8, v8, v6
	v_cmp_eq_u32_e32 vcc, 0, v14
	s_waitcnt lgkmcnt(0)
	v_fma_f32 v5, v5, -v7, v8
	v_cndmask_b32_e32 v5, v5, v6, vcc
	v_add_u32_e32 v6, -2, v191
	v_cmp_lt_i32_e32 vcc, v6, v47
	s_nop 1
	v_cndmask_b32_e32 v6, v6, v191, vcc
	v_lshlrev_b32_e32 v6, 2, v6
	ds_bpermute_b32 v6, v6, v5
	v_cmp_gt_u32_e32 vcc, 2, v14
	s_waitcnt lgkmcnt(0)
	v_add_f32_e32 v6, v5, v6
	v_cndmask_b32_e32 v5, v6, v5, vcc
	v_add_u32_e32 v6, -4, v191
	v_cmp_lt_i32_e32 vcc, v6, v47
	s_nop 1
	v_cndmask_b32_e32 v6, v6, v191, vcc
	v_lshlrev_b32_e32 v6, 2, v6
	ds_bpermute_b32 v6, v6, v5
	v_cmp_gt_u32_e32 vcc, 4, v14
	s_waitcnt lgkmcnt(0)
	v_add_f32_e32 v6, v5, v6
	v_cndmask_b32_e32 v5, v6, v5, vcc
	v_add_u32_e32 v6, -8, v191
	v_cmp_lt_i32_e32 vcc, v6, v47
	s_nop 1
	v_cndmask_b32_e32 v6, v6, v191, vcc
	v_lshlrev_b32_e32 v6, 2, v6
	ds_bpermute_b32 v6, v6, v5
	v_cmp_gt_u32_e32 vcc, 8, v14
	s_waitcnt lgkmcnt(0)
	v_add_f32_e32 v6, v5, v6
	v_cndmask_b32_e32 v5, v6, v5, vcc
	v_add_u32_e32 v6, -16, v191
	v_cmp_lt_i32_e32 vcc, v6, v47
	s_nop 1
	v_cndmask_b32_e32 v6, v6, v191, vcc
	v_lshlrev_b32_e32 v6, 2, v6
	ds_bpermute_b32 v6, v6, v5
	v_cmp_gt_u32_e32 vcc, 16, v14
	s_waitcnt lgkmcnt(0)
	v_add_f32_e32 v6, v5, v6
	v_cndmask_b32_e32 v5, v6, v5, vcc
	v_subrev_u32_e32 v6, 32, v191
	v_cmp_lt_i32_e32 vcc, v6, v47
	s_nop 1
	v_cndmask_b32_e32 v6, v6, v191, vcc
	v_lshlrev_b32_e32 v6, 2, v6
	ds_bpermute_b32 v6, v6, v5
	v_cmp_gt_u32_e32 vcc, 32, v14
	s_waitcnt lgkmcnt(0)
	v_add_f32_e32 v6, v5, v6
	v_cndmask_b32_e32 v6, v6, v5, vcc
	v_lshlrev_b32_e32 v5, 2, v194
	v_add_u32_e32 v7, v15, v5
	ds_write_b32 v7, v6
	v_add_u32_e32 v7, v13, v5
	ds_write_b32 v7, v4
	v_mul_f32_e32 v7, 0x3fb8aa3b, v6
	v_exp_f32_e32 v7, v7
	v_add_u32_e32 v5, v12, v5
	v_mul_f32_e32 v4, v4, v7
	ds_write_b32 v5, v4
	v_or_b32_e32 v4, v3, v16
	v_ashrrev_i32_e32 v5, 31, v4
	v_lshlrev_b64 v[4:5], 15, v[4:5]
	v_lshl_add_u64 v[4:5], s[4:5], 0, v[4:5]
	v_lshl_add_u64 v[4:5], v[4:5], 0, v[20:21]
	v_lshl_add_u64 v[0:1], v[4:5], 0, v[0:1]
	global_store_dword v[0:1], v6, off
	v_mov_b32_e32 v0, 0x8800
